# v38 + nt hint on P5 gate (read-once) epilogue loads
# baseline (speedup 1.0000x reference)
;     __device__ __forceinline__ void operator()(const f32x4 (&acc)[2][2][4][2], const Unit& u, int wr, int wc, int fr, int fq) const {
;     ...
;         bf16_t* obase = (bf16_t*)O + (size_t)(u.pm * BM + wr * 64 + (L >> 3)) * ldc + u.pn * BM + wc * 64 + 8 * (L & 7);
; #pragma unroll
;         for (int g = 0; g < 8; ++g) {
;             const int ai = g >> 2, m = g & 3;
;             const int row = row0 + ai * HALF + m * 16;
; #pragma unroll
;             for (int bj = 0; bj < 2; ++bj) {
;                 const int col = col0 + bj * 32;
;                 f32x4 v0 = acc[ai][bj][m][0], v1 = acc[ai][bj][m][1];
;                 if (MODE == 1) {
;                     if (special) {
;                         const f32x4 b0 = *(const GAS1 f32x4*)(bias + col) * -1.4426950408889634f, b1 = *(const GAS1 f32x4*)(bias + col + 4) * -1.4426950408889634f;
; #pragma unroll
;                         for (int j = 0; j < 4; ++j) { v0[j] = __builtin_amdgcn_rcpf(1.0f + __builtin_amdgcn_exp2f(__builtin_fmaf(v0[j], -1.4426950408889634f, b0[j])));
;                                                       v1[j] = __builtin_amdgcn_rcpf(1.0f + __builtin_amdgcn_exp2f(__builtin_fmaf(v1[j], -1.4426950408889634f, b1[j]))); }
;                     }
;                 }
;                 if (MODE == 2) {
;                     if (special) {
;                         const int fi = ((col & 63) >> 3) * 4;
;                         const f32x4 c = *(const GAS1 f32x4*)(cosT + (size_t)row * 32 + fi), s_ = *(const GAS1 f32x4*)(sinT + (size_t)row * 32 + fi);
;                         const f32x4 o1 = v0 * c - v1 * s_, o2 = v1 * c + v0 * s_; v0 = o1; v1 = o2;
;                     }
;                 }
;                 if (MODE == 3 || MODE == 4) {
;                     const u32x4 gw = *(const GAS1 u32x4*)(G + (size_t)row * ldg + col);
;                     const f32x4 g0 = {bf_lo(gw.x), bf_hi(gw.x), bf_lo(gw.y), bf_hi(gw.y)}, g1 = {bf_lo(gw.z), bf_hi(gw.z), bf_lo(gw.w), bf_hi(gw.w)};
;                     v0 = v0 * g0; v1 = v1 * g1;
;                     if (MODE == 4) {
;                         const u32x4 ow = *(const GAS1 u32x4*)((const bf16_t*)O + (size_t)row * ldc + col);
;                         const f32x4 o0 = {bf_lo(ow.x), bf_hi(ow.x), bf_lo(ow.y), bf_hi(ow.y)}, o1 = {bf_lo(ow.z), bf_hi(ow.z), bf_lo(ow.w), bf_hi(ow.w)};
;                         v0 += o0; v1 += o1;
;                     }
.LBB0_1410:
	s_lshl_b32 s25, s34, 8
	s_lshl_b32 s34, s35, 8
	s_add_i32 s25, s25, s65
	v_or_b32_e32 v148, s34, v153
	v_or_b32_e32 v159, s25, v150
	v_mov_b64_e32 v[146:147], s[18:19]
	v_ashrrev_i32_e32 v149, 31, v148
	v_mad_i64_i32 v[160:161], s[36:37], v159, s74, v[146:147]
	v_lshlrev_b64 v[148:149], 1, v[148:149]
	v_lshl_add_u64 v[164:165], v[160:161], 0, v[148:149]
	v_add_u32_e32 v234, 0, v159
	v_mad_i64_i32 v[206:207], s[98:99], v234, s74, v[146:147]
	v_lshl_add_u64 v[206:207], v[206:207], 0, v[148:149]
	global_load_dwordx4 v[176:179], v[206:207], off nt
	global_load_dwordx4 v[180:183], v[206:207], off offset:64 nt
	v_add_u32_e32 v234, 16, v159
	v_mad_i64_i32 v[206:207], s[98:99], v234, s74, v[146:147]
	v_lshl_add_u64 v[206:207], v[206:207], 0, v[148:149]
	global_load_dwordx4 v[184:187], v[206:207], off nt
	global_load_dwordx4 v[188:191], v[206:207], off offset:64 nt
	v_add_u32_e32 v234, 32, v159
	v_mad_i64_i32 v[206:207], s[98:99], v234, s74, v[146:147]
	v_lshl_add_u64 v[206:207], v[206:207], 0, v[148:149]
	global_load_dwordx4 v[192:195], v[206:207], off nt
	global_load_dwordx4 v[196:199], v[206:207], off offset:64 nt
	v_add_u32_e32 v234, 48, v159
	v_mad_i64_i32 v[206:207], s[98:99], v234, s74, v[146:147]
	v_lshl_add_u64 v[206:207], v[206:207], 0, v[148:149]
	global_load_dwordx4 v[202:205], v[206:207], off nt
	global_load_dwordx4 v[210:213], v[206:207], off offset:64 nt
	v_add_u32_e32 v234, 128, v159
	v_mad_i64_i32 v[206:207], s[98:99], v234, s74, v[146:147]
	v_lshl_add_u64 v[206:207], v[206:207], 0, v[148:149]
	global_load_dwordx4 v[214:217], v[206:207], off nt
	global_load_dwordx4 v[218:221], v[206:207], off offset:64 nt
	v_add_u32_e32 v234, 144, v159
	v_mad_i64_i32 v[206:207], s[98:99], v234, s74, v[146:147]
	v_lshl_add_u64 v[206:207], v[206:207], 0, v[148:149]
	global_load_dwordx4 v[222:225], v[206:207], off nt
	global_load_dwordx4 v[226:229], v[206:207], off offset:64 nt
	v_add_u32_e32 v234, 160, v159
	v_mad_i64_i32 v[206:207], s[98:99], v234, s74, v[146:147]
	v_lshl_add_u64 v[206:207], v[206:207], 0, v[148:149]
	global_load_dwordx4 v[236:239], v[206:207], off nt
	global_load_dwordx4 v[240:243], v[206:207], off offset:64 nt
	v_add_u32_e32 v234, 176, v159
	v_mad_i64_i32 v[206:207], s[98:99], v234, s74, v[146:147]
	v_lshl_add_u64 v[206:207], v[206:207], 0, v[148:149]
	global_load_dwordx4 v[246:249], v[206:207], off nt
	global_load_dwordx4 v[250:253], v[206:207], off offset:64 nt
	s_ashr_i32 s35, s34, 31
	s_waitcnt vmcnt(15)
	v_mov_b32_e32 v160, v176
	v_mov_b32_e32 v161, v177
	v_mov_b32_e32 v162, v178
	v_mov_b32_e32 v163, v179
	v_lshlrev_b32_e32 v166, 16, v160
	v_and_b32_e32 v167, 0xffff0000, v160
	v_lshlrev_b32_e32 v160, 16, v161
	v_and_b32_e32 v161, 0xffff0000, v161
	v_lshlrev_b32_e32 v168, 16, v162
	v_and_b32_e32 v169, 0xffff0000, v162
	v_lshlrev_b32_e32 v162, 16, v163
	v_and_b32_e32 v163, 0xffff0000, v163
	v_pk_mul_f32 v[126:127], v[126:127], v[160:161]
	v_pk_mul_f32 v[160:161], v[122:123], v[162:163]
	v_pk_mul_f32 v[122:123], v[120:121], v[168:169]
	v_pk_mul_f32 v[124:125], v[124:125], v[166:167]
	s_nop 0
	v_cvt_pk_bf16_f32 v120, v124, v125
	v_cvt_pk_bf16_f32 v121, v126, v127
	v_cvt_pk_bf16_f32 v122, v122, v123
	v_cvt_pk_bf16_f32 v123, v160, v161
	v_or_b32_e32 v124, 16, v159
	ds_write_b128 v154, v[120:123]
	v_mad_i64_i32 v[124:125], s[36:37], v124, s74, v[146:147]
	v_lshl_add_u64 v[124:125], v[124:125], 0, v[148:149]
	s_waitcnt vmcnt(14)
	v_mov_b32_e32 v120, v180
	v_mov_b32_e32 v121, v181
	v_mov_b32_e32 v122, v182
	v_mov_b32_e32 v123, v183
	v_lshlrev_b32_e32 v126, 16, v120
	v_and_b32_e32 v127, 0xffff0000, v120
	v_lshlrev_b32_e32 v120, 16, v121
	v_and_b32_e32 v121, 0xffff0000, v121
	v_lshlrev_b32_e32 v160, 16, v122
	v_and_b32_e32 v161, 0xffff0000, v122
	v_lshlrev_b32_e32 v122, 16, v123
	v_and_b32_e32 v123, 0xffff0000, v123
	v_pk_mul_f32 v[118:119], v[118:119], v[120:121]
	v_pk_mul_f32 v[120:121], v[110:111], v[122:123]
	v_pk_mul_f32 v[110:111], v[108:109], v[160:161]
	v_pk_mul_f32 v[116:117], v[116:117], v[126:127]
	s_nop 0
	v_cvt_pk_bf16_f32 v108, v116, v117
	v_cvt_pk_bf16_f32 v109, v118, v119
	v_cvt_pk_bf16_f32 v110, v110, v111
	v_cvt_pk_bf16_f32 v111, v120, v121
	s_nop 0
	ds_write_b128 v154, v[108:111] offset:64
	ds_read_b128 v[108:111], v155
	ds_read_b128 v[116:119], v155 offset:1152
	s_waitcnt vmcnt(13)
	v_mov_b32_e32 v120, v184
	v_mov_b32_e32 v121, v185
	v_mov_b32_e32 v122, v186
	v_mov_b32_e32 v123, v187
	v_lshlrev_b32_e32 v126, 16, v120
	v_and_b32_e32 v127, 0xffff0000, v120
	v_lshlrev_b32_e32 v120, 16, v121
	v_and_b32_e32 v121, 0xffff0000, v121
	v_lshlrev_b32_e32 v160, 16, v122
	v_and_b32_e32 v161, 0xffff0000, v122
	v_lshlrev_b32_e32 v122, 16, v123
	v_and_b32_e32 v123, 0xffff0000, v123
	v_pk_mul_f32 v[114:115], v[114:115], v[120:121]
	v_pk_mul_f32 v[112:113], v[112:113], v[126:127]
	v_pk_mul_f32 v[120:121], v[106:107], v[122:123]
	v_pk_mul_f32 v[106:107], v[104:105], v[160:161]
	v_cvt_pk_bf16_f32 v104, v112, v113
	v_cvt_pk_bf16_f32 v105, v114, v115
	s_nop 0
	v_cvt_pk_bf16_f32 v106, v106, v107
	v_cvt_pk_bf16_f32 v107, v120, v121
	s_nop 0
	ds_write_b128 v154, v[104:107]
	v_or_b32_e32 v104, s25, v152
	v_ashrrev_i32_e32 v105, 31, v104
	v_lshlrev_b64 v[104:105], 12, v[104:105]
	v_lshl_add_u64 v[104:105], s[8:9], 0, v[104:105]
	v_lshl_add_u64 v[104:105], s[34:35], 1, v[104:105]
	v_or_b32_e32 v106, 32, v159
	v_lshl_add_u64 v[104:105], v[104:105], 0, s[12:13]
	v_mad_i64_i32 v[106:107], s[36:37], v106, s74, v[146:147]
	v_lshl_add_u64 v[104:105], v[104:105], 0, v[136:137]
	v_lshl_add_u64 v[120:121], v[106:107], 0, v[148:149]
	v_add_co_u32_e32 v106, vcc, s69, v104
	s_waitcnt vmcnt(12)
; __device__ __forceinline__ unsigned cvt_pk_bf16(float lo, float hi) { unsigned r; asm volatile("v_cvt_pk_bf16_f32 %0, %1, %2" : "=v"(r) : "v"(lo), "v"(hi)); return r; }
; __device__ __forceinline__ float bf_lo(unsigned w) { return __uint_as_float(w << 16); }
; __device__ __forceinline__ float bf_hi(unsigned w) { return __uint_as_float(w & 0xffff0000u); }
; #define GAS1 __attribute__((address_space(1)))
;     __device__ __forceinline__ void operator()(const f32x4 (&acc)[2][2][4][2], const Unit& u, int wr, int wc, int fr, int fq) const {
;     ...
;                 if (MODE == 3 || MODE == 4) {
;                     const u32x4 gw = *(const GAS1 u32x4*)(G + (size_t)row * ldg + col);
;                     const f32x4 g0 = {bf_lo(gw.x), bf_hi(gw.x), bf_lo(gw.y), bf_hi(gw.y)}, g1 = {bf_lo(gw.z), bf_hi(gw.z), bf_lo(gw.w), bf_hi(gw.w)};
;                     v0 = v0 * g0; v1 = v1 * g1;
;                     if (MODE == 4) {
;                         const u32x4 ow = *(const GAS1 u32x4*)((const bf16_t*)O + (size_t)row * ldc + col);
;                         const f32x4 o0 = {bf_lo(ow.x), bf_hi(ow.x), bf_lo(ow.y), bf_hi(ow.y)}, o1 = {bf_lo(ow.z), bf_hi(ow.z), bf_lo(ow.w), bf_hi(ow.w)};
;                         v0 += o0; v1 += o1;
;                     }
;                 }
;                 u32x4 w; w.x = cvt_pk_bf16(v0[0], v0[1]); w.y = cvt_pk_bf16(v0[2], v0[3]); w.z = cvt_pk_bf16(v1[0], v1[1]); w.w = cvt_pk_bf16(v1[2], v1[3]);
;                 if (bj == 0) asm volatile("ds_write_b128 %0, %1" :: "v"(wa), "v"(w)); else asm volatile("ds_write_b128 %0, %1 offset:64" :: "v"(wa), "v"(w));
;             }
;             asm volatile("ds_read_b128 %0, %1" : "=&v"(rb[g & 1][0]) : "v"(ra));
;             asm volatile("ds_read_b128 %0, %1 offset:1152" : "=&v"(rb[g & 1][1]) : "v"(ra));
;             if (g >= 1) {
;                 asm volatile("s_waitcnt lgkmcnt(4)" : "+v"(rb[(g - 1) & 1][0]), "+v"(rb[(g - 1) & 1][1]));
;                 bf16_t* ob = obase + (size_t)(((g - 1) >> 2) * HALF + ((g - 1) & 3) * 16) * ldc;
;                 *(GAS1 u32x4*)ob = rb[(g - 1) & 1][0]; *(GAS1 u32x4*)(ob + (size_t)8 * ldc) = rb[(g - 1) & 1][1];
	v_mov_b32_e32 v112, v188
	v_mov_b32_e32 v113, v189
	v_mov_b32_e32 v114, v190
	v_mov_b32_e32 v115, v191
	v_lshlrev_b32_e32 v122, 16, v112
	v_and_b32_e32 v123, 0xffff0000, v112
	v_lshlrev_b32_e32 v112, 16, v113
	v_and_b32_e32 v113, 0xffff0000, v113
	v_lshlrev_b32_e32 v124, 16, v114
	v_and_b32_e32 v125, 0xffff0000, v114
	v_lshlrev_b32_e32 v114, 16, v115
	v_and_b32_e32 v115, 0xffff0000, v115
	v_pk_mul_f32 v[102:103], v[102:103], v[112:113]
	v_pk_mul_f32 v[112:113], v[94:95], v[114:115]
	v_pk_mul_f32 v[94:95], v[92:93], v[124:125]
	v_pk_mul_f32 v[100:101], v[100:101], v[122:123]
	v_addc_co_u32_e32 v107, vcc, 0, v105, vcc
	v_cvt_pk_bf16_f32 v92, v100, v101
	v_cvt_pk_bf16_f32 v93, v102, v103
	v_cvt_pk_bf16_f32 v94, v94, v95
	v_cvt_pk_bf16_f32 v95, v112, v113
	s_nop 0
	ds_write_b128 v154, v[92:95] offset:64
	ds_read_b128 v[92:95], v155
	ds_read_b128 v[100:103], v155 offset:1152
	s_waitcnt lgkmcnt(4)
	global_store_dwordx4 v[104:105], v[108:111], off nt
	global_store_dwordx4 v[106:107], v[116:119], off nt
	s_waitcnt vmcnt(13)
	v_mov_b32_e32 v106, v192
	v_mov_b32_e32 v107, v193
	v_mov_b32_e32 v108, v194
	v_mov_b32_e32 v109, v195
	v_lshlrev_b32_e32 v110, 16, v106
	v_and_b32_e32 v111, 0xffff0000, v106
	v_lshlrev_b32_e32 v106, 16, v107
	v_and_b32_e32 v107, 0xffff0000, v107
	v_lshlrev_b32_e32 v112, 16, v108
	v_and_b32_e32 v113, 0xffff0000, v108
	v_lshlrev_b32_e32 v108, 16, v109
	v_and_b32_e32 v109, 0xffff0000, v109
	v_pk_mul_f32 v[98:99], v[98:99], v[106:107]
	v_pk_mul_f32 v[106:107], v[90:91], v[108:109]
	v_pk_mul_f32 v[90:91], v[88:89], v[112:113]
	v_pk_mul_f32 v[96:97], v[96:97], v[110:111]
	s_nop 0
	v_cvt_pk_bf16_f32 v88, v96, v97
	v_cvt_pk_bf16_f32 v89, v98, v99
	v_cvt_pk_bf16_f32 v90, v90, v91
	v_cvt_pk_bf16_f32 v91, v106, v107
	v_add_co_u32_e32 v98, vcc, s64, v104
	ds_write_b128 v154, v[88:91]
	v_or_b32_e32 v96, 48, v159
	v_addc_co_u32_e32 v99, vcc, 0, v105, vcc
	v_mad_i64_i32 v[96:97], s[34:35], v96, s74, v[146:147]
	v_add_co_u32_e32 v106, vcc, s68, v104
	v_lshl_add_u64 v[96:97], v[96:97], 0, v[148:149]
	s_nop 0
	v_addc_co_u32_e32 v107, vcc, 0, v105, vcc
	s_waitcnt vmcnt(12)
	v_mov_b32_e32 v88, v196
	v_mov_b32_e32 v89, v197
	v_mov_b32_e32 v90, v198
	v_mov_b32_e32 v91, v199
	v_lshlrev_b32_e32 v108, 16, v88
	v_and_b32_e32 v109, 0xffff0000, v88
	v_lshlrev_b32_e32 v88, 16, v89
	v_and_b32_e32 v89, 0xffff0000, v89
	v_lshlrev_b32_e32 v110, 16, v90
	v_and_b32_e32 v111, 0xffff0000, v90
	v_lshlrev_b32_e32 v90, 16, v91
	v_and_b32_e32 v91, 0xffff0000, v91
	v_pk_mul_f32 v[86:87], v[86:87], v[88:89]
	v_pk_mul_f32 v[88:89], v[78:79], v[90:91]
	v_pk_mul_f32 v[78:79], v[76:77], v[110:111]
	v_pk_mul_f32 v[84:85], v[84:85], v[108:109]
	s_nop 0
	v_cvt_pk_bf16_f32 v76, v84, v85
	v_cvt_pk_bf16_f32 v77, v86, v87
	v_cvt_pk_bf16_f32 v78, v78, v79
	v_cvt_pk_bf16_f32 v79, v88, v89
	s_nop 0
	ds_write_b128 v154, v[76:79] offset:64
	ds_read_b128 v[76:79], v155
	ds_read_b128 v[84:87], v155 offset:1152
	s_waitcnt lgkmcnt(4)
	global_store_dwordx4 v[98:99], v[92:95], off nt
	global_store_dwordx4 v[106:107], v[100:103], off nt
	s_waitcnt vmcnt(13)
	v_mov_b32_e32 v88, v202
	v_mov_b32_e32 v89, v203
	v_mov_b32_e32 v90, v204
	v_mov_b32_e32 v91, v205
	v_lshlrev_b32_e32 v92, 16, v88
	v_and_b32_e32 v93, 0xffff0000, v88
	v_lshlrev_b32_e32 v88, 16, v89
	v_and_b32_e32 v89, 0xffff0000, v89
	v_lshlrev_b32_e32 v94, 16, v90
	v_and_b32_e32 v95, 0xffff0000, v90
	v_lshlrev_b32_e32 v90, 16, v91
	v_and_b32_e32 v91, 0xffff0000, v91
	v_pk_mul_f32 v[82:83], v[82:83], v[88:89]
	v_pk_mul_f32 v[88:89], v[74:75], v[90:91]
	v_pk_mul_f32 v[74:75], v[72:73], v[94:95]
	v_pk_mul_f32 v[80:81], v[80:81], v[92:93]
	s_nop 0
	v_cvt_pk_bf16_f32 v72, v80, v81
	v_cvt_pk_bf16_f32 v73, v82, v83
	v_cvt_pk_bf16_f32 v74, v74, v75
	v_cvt_pk_bf16_f32 v75, v88, v89
	v_add_co_u32_e32 v82, vcc, s75, v104
	ds_write_b128 v154, v[72:75]
	v_add_u32_e32 v80, 0x80, v159
	v_addc_co_u32_e32 v83, vcc, 0, v105, vcc
	v_mad_i64_i32 v[80:81], s[34:35], v80, s74, v[146:147]
	v_add_co_u32_e32 v88, vcc, s76, v104
	v_lshl_add_u64 v[80:81], v[80:81], 0, v[148:149]
	s_nop 0
	v_addc_co_u32_e32 v89, vcc, 0, v105, vcc
	s_waitcnt vmcnt(12)
	v_mov_b32_e32 v72, v210
	v_mov_b32_e32 v73, v211
	v_mov_b32_e32 v74, v212
	v_mov_b32_e32 v75, v213
	v_lshlrev_b32_e32 v90, 16, v72
	v_and_b32_e32 v91, 0xffff0000, v72
	v_lshlrev_b32_e32 v72, 16, v73
	v_and_b32_e32 v73, 0xffff0000, v73
	v_lshlrev_b32_e32 v92, 16, v74
	v_and_b32_e32 v93, 0xffff0000, v74
	v_lshlrev_b32_e32 v74, 16, v75
	v_and_b32_e32 v75, 0xffff0000, v75
	v_pk_mul_f32 v[70:71], v[70:71], v[72:73]
	v_pk_mul_f32 v[72:73], v[66:67], v[74:75]
	v_pk_mul_f32 v[66:67], v[64:65], v[92:93]
	v_pk_mul_f32 v[68:69], v[68:69], v[90:91]
	s_nop 0
	v_cvt_pk_bf16_f32 v64, v68, v69
	v_cvt_pk_bf16_f32 v65, v70, v71
	v_cvt_pk_bf16_f32 v66, v66, v67
	v_cvt_pk_bf16_f32 v67, v72, v73
	s_nop 0
	ds_write_b128 v154, v[64:67] offset:64
	ds_read_b128 v[64:67], v155
	ds_read_b128 v[68:71], v155 offset:1152
	s_waitcnt lgkmcnt(4)
	global_store_dwordx4 v[82:83], v[76:79], off nt
	global_store_dwordx4 v[88:89], v[84:87], off nt
	s_waitcnt vmcnt(13)
	v_mov_b32_e32 v72, v214
	v_mov_b32_e32 v73, v215
	v_mov_b32_e32 v74, v216
	v_mov_b32_e32 v75, v217
	v_lshlrev_b32_e32 v76, 16, v72
	v_and_b32_e32 v77, 0xffff0000, v72
	v_lshlrev_b32_e32 v72, 16, v73
	v_and_b32_e32 v73, 0xffff0000, v73
	v_lshlrev_b32_e32 v78, 16, v74
	v_and_b32_e32 v79, 0xffff0000, v74
	v_lshlrev_b32_e32 v74, 16, v75
	v_and_b32_e32 v75, 0xffff0000, v75
	v_pk_mul_f32 v[62:63], v[62:63], v[72:73]
	v_pk_mul_f32 v[72:73], v[58:59], v[74:75]
	v_pk_mul_f32 v[58:59], v[56:57], v[78:79]
	v_pk_mul_f32 v[60:61], v[60:61], v[76:77]
	s_nop 0
	v_cvt_pk_bf16_f32 v56, v60, v61
	v_cvt_pk_bf16_f32 v57, v62, v63
	v_cvt_pk_bf16_f32 v58, v58, v59
	v_cvt_pk_bf16_f32 v59, v72, v73
	v_add_co_u32_e32 v62, vcc, s77, v104
	ds_write_b128 v154, v[56:59]
	v_add_u32_e32 v60, 0x90, v159
	v_addc_co_u32_e32 v63, vcc, 0, v105, vcc
	v_mad_i64_i32 v[60:61], s[34:35], v60, s74, v[146:147]
	v_add_co_u32_e32 v72, vcc, s79, v104
	v_lshl_add_u64 v[60:61], v[60:61], 0, v[148:149]
	s_nop 0
	v_addc_co_u32_e32 v73, vcc, 0, v105, vcc
	s_waitcnt vmcnt(12)
; __device__ __forceinline__ unsigned cvt_pk_bf16(float lo, float hi) { unsigned r; asm volatile("v_cvt_pk_bf16_f32 %0, %1, %2" : "=v"(r) : "v"(lo), "v"(hi)); return r; }
; __device__ __forceinline__ float bf_lo(unsigned w) { return __uint_as_float(w << 16); }
; __device__ __forceinline__ float bf_hi(unsigned w) { return __uint_as_float(w & 0xffff0000u); }
; #define GAS1 __attribute__((address_space(1)))
;     __device__ __forceinline__ void operator()(const f32x4 (&acc)[2][2][4][2], const Unit& u, int wr, int wc, int fr, int fq) const {
;     ...
;                 if (MODE == 3 || MODE == 4) {
;                     const u32x4 gw = *(const GAS1 u32x4*)(G + (size_t)row * ldg + col);
;                     const f32x4 g0 = {bf_lo(gw.x), bf_hi(gw.x), bf_lo(gw.y), bf_hi(gw.y)}, g1 = {bf_lo(gw.z), bf_hi(gw.z), bf_lo(gw.w), bf_hi(gw.w)};
;                     v0 = v0 * g0; v1 = v1 * g1;
;                     if (MODE == 4) {
;                         const u32x4 ow = *(const GAS1 u32x4*)((const bf16_t*)O + (size_t)row * ldc + col);
;                         const f32x4 o0 = {bf_lo(ow.x), bf_hi(ow.x), bf_lo(ow.y), bf_hi(ow.y)}, o1 = {bf_lo(ow.z), bf_hi(ow.z), bf_lo(ow.w), bf_hi(ow.w)};
;                         v0 += o0; v1 += o1;
;                     }
;                 }
;                 u32x4 w; w.x = cvt_pk_bf16(v0[0], v0[1]); w.y = cvt_pk_bf16(v0[2], v0[3]); w.z = cvt_pk_bf16(v1[0], v1[1]); w.w = cvt_pk_bf16(v1[2], v1[3]);
;                 if (bj == 0) asm volatile("ds_write_b128 %0, %1" :: "v"(wa), "v"(w)); else asm volatile("ds_write_b128 %0, %1 offset:64" :: "v"(wa), "v"(w));
;             }
;             asm volatile("ds_read_b128 %0, %1" : "=&v"(rb[g & 1][0]) : "v"(ra));
;             asm volatile("ds_read_b128 %0, %1 offset:1152" : "=&v"(rb[g & 1][1]) : "v"(ra));
;             if (g >= 1) {
;                 asm volatile("s_waitcnt lgkmcnt(4)" : "+v"(rb[(g - 1) & 1][0]), "+v"(rb[(g - 1) & 1][1]));
;                 bf16_t* ob = obase + (size_t)(((g - 1) >> 2) * HALF + ((g - 1) & 3) * 16) * ldc;
;                 *(GAS1 u32x4*)ob = rb[(g - 1) & 1][0]; *(GAS1 u32x4*)(ob + (size_t)8 * ldc) = rb[(g - 1) & 1][1];
	v_mov_b32_e32 v56, v218
	v_mov_b32_e32 v57, v219
	v_mov_b32_e32 v58, v220
	v_mov_b32_e32 v59, v221
	v_lshlrev_b32_e32 v74, 16, v56
	v_and_b32_e32 v75, 0xffff0000, v56
	v_lshlrev_b32_e32 v56, 16, v57
	v_and_b32_e32 v57, 0xffff0000, v57
	v_lshlrev_b32_e32 v76, 16, v58
	v_and_b32_e32 v77, 0xffff0000, v58
	v_lshlrev_b32_e32 v58, 16, v59
	v_and_b32_e32 v59, 0xffff0000, v59
	v_pk_mul_f32 v[54:55], v[54:55], v[56:57]
	v_pk_mul_f32 v[56:57], v[46:47], v[58:59]
	v_pk_mul_f32 v[46:47], v[44:45], v[76:77]
	v_pk_mul_f32 v[52:53], v[52:53], v[74:75]
	s_nop 0
	v_cvt_pk_bf16_f32 v44, v52, v53
	v_cvt_pk_bf16_f32 v45, v54, v55
	v_cvt_pk_bf16_f32 v46, v46, v47
	v_cvt_pk_bf16_f32 v47, v56, v57
	s_nop 0
	ds_write_b128 v154, v[44:47] offset:64
	ds_read_b128 v[44:47], v155
	ds_read_b128 v[52:55], v155 offset:1152
	s_waitcnt lgkmcnt(4)
	global_store_dwordx4 v[62:63], v[64:67], off nt
	global_store_dwordx4 v[72:73], v[68:71], off nt
	s_waitcnt vmcnt(13)
	v_mov_b32_e32 v56, v222
	v_mov_b32_e32 v57, v223
	v_mov_b32_e32 v58, v224
	v_mov_b32_e32 v59, v225
	v_lshlrev_b32_e32 v62, 16, v56
	v_and_b32_e32 v63, 0xffff0000, v56
	v_lshlrev_b32_e32 v56, 16, v57
	v_and_b32_e32 v57, 0xffff0000, v57
	v_lshlrev_b32_e32 v64, 16, v58
	v_and_b32_e32 v65, 0xffff0000, v58
	v_lshlrev_b32_e32 v58, 16, v59
	v_and_b32_e32 v59, 0xffff0000, v59
	v_pk_mul_f32 v[50:51], v[50:51], v[56:57]
	v_pk_mul_f32 v[56:57], v[42:43], v[58:59]
	v_pk_mul_f32 v[42:43], v[40:41], v[64:65]
	v_pk_mul_f32 v[48:49], v[48:49], v[62:63]
	s_nop 0
	v_cvt_pk_bf16_f32 v40, v48, v49
	v_cvt_pk_bf16_f32 v41, v50, v51
	v_cvt_pk_bf16_f32 v42, v42, v43
	v_cvt_pk_bf16_f32 v43, v56, v57
	v_add_co_u32_e32 v50, vcc, s80, v104
	ds_write_b128 v154, v[40:43]
	v_add_u32_e32 v48, 0xa0, v159
	v_addc_co_u32_e32 v51, vcc, 0, v105, vcc
	v_mad_i64_i32 v[48:49], s[34:35], v48, s74, v[146:147]
	v_add_co_u32_e32 v56, vcc, s81, v104
	v_lshl_add_u64 v[48:49], v[48:49], 0, v[148:149]
	s_nop 0
	v_addc_co_u32_e32 v57, vcc, 0, v105, vcc
	s_waitcnt vmcnt(12)
	v_mov_b32_e32 v40, v226
	v_mov_b32_e32 v41, v227
	v_mov_b32_e32 v42, v228
	v_mov_b32_e32 v43, v229
	v_lshlrev_b32_e32 v58, 16, v40
	v_and_b32_e32 v59, 0xffff0000, v40
	v_lshlrev_b32_e32 v40, 16, v41
	v_and_b32_e32 v41, 0xffff0000, v41
	v_lshlrev_b32_e32 v60, 16, v42
	v_and_b32_e32 v61, 0xffff0000, v42
	v_lshlrev_b32_e32 v42, 16, v43
	v_and_b32_e32 v43, 0xffff0000, v43
	v_pk_mul_f32 v[38:39], v[38:39], v[40:41]
	v_pk_mul_f32 v[40:41], v[30:31], v[42:43]
	v_pk_mul_f32 v[30:31], v[28:29], v[60:61]
	v_pk_mul_f32 v[36:37], v[36:37], v[58:59]
	s_nop 0
	v_cvt_pk_bf16_f32 v28, v36, v37
	v_cvt_pk_bf16_f32 v29, v38, v39
	v_cvt_pk_bf16_f32 v30, v30, v31
	v_cvt_pk_bf16_f32 v31, v40, v41
	s_nop 0
	ds_write_b128 v154, v[28:31] offset:64
	ds_read_b128 v[28:31], v155
	ds_read_b128 v[36:39], v155 offset:1152
	s_waitcnt lgkmcnt(4)
	global_store_dwordx4 v[50:51], v[44:47], off nt
	global_store_dwordx4 v[56:57], v[52:55], off nt
	s_waitcnt vmcnt(13)
	v_mov_b32_e32 v40, v236
	v_mov_b32_e32 v41, v237
	v_mov_b32_e32 v42, v238
	v_mov_b32_e32 v43, v239
	v_lshlrev_b32_e32 v44, 16, v40
	v_and_b32_e32 v45, 0xffff0000, v40
	v_lshlrev_b32_e32 v40, 16, v41
	v_and_b32_e32 v41, 0xffff0000, v41
	v_lshlrev_b32_e32 v46, 16, v42
	v_and_b32_e32 v47, 0xffff0000, v42
	v_lshlrev_b32_e32 v42, 16, v43
	v_and_b32_e32 v43, 0xffff0000, v43
	v_pk_mul_f32 v[34:35], v[34:35], v[40:41]
	v_pk_mul_f32 v[40:41], v[26:27], v[42:43]
	v_pk_mul_f32 v[26:27], v[24:25], v[46:47]
	v_pk_mul_f32 v[32:33], v[32:33], v[44:45]
	s_nop 0
	v_cvt_pk_bf16_f32 v24, v32, v33
	v_cvt_pk_bf16_f32 v25, v34, v35
	v_cvt_pk_bf16_f32 v26, v26, v27
	v_cvt_pk_bf16_f32 v27, v40, v41
	v_add_co_u32_e32 v34, vcc, s82, v104
	ds_write_b128 v154, v[24:27]
	v_add_u32_e32 v32, 0xb0, v159
	v_addc_co_u32_e32 v35, vcc, 0, v105, vcc
	v_mad_i64_i32 v[32:33], s[34:35], v32, s74, v[146:147]
	v_add_co_u32_e32 v40, vcc, s83, v104
	v_lshl_add_u64 v[32:33], v[32:33], 0, v[148:149]
	s_nop 0
	v_addc_co_u32_e32 v41, vcc, 0, v105, vcc
	s_waitcnt vmcnt(12)
; __device__ __forceinline__ unsigned cvt_pk_bf16(float lo, float hi) { unsigned r; asm volatile("v_cvt_pk_bf16_f32 %0, %1, %2" : "=v"(r) : "v"(lo), "v"(hi)); return r; }
; __device__ __forceinline__ float bf_lo(unsigned w) { return __uint_as_float(w << 16); }
; __device__ __forceinline__ float bf_hi(unsigned w) { return __uint_as_float(w & 0xffff0000u); }
; #define GAS1 __attribute__((address_space(1)))
;     __device__ __forceinline__ void operator()(const f32x4 (&acc)[2][2][4][2], const Unit& u, int wr, int wc, int fr, int fq) const {
;     ...
;                 if (MODE == 3 || MODE == 4) {
;                     const u32x4 gw = *(const GAS1 u32x4*)(G + (size_t)row * ldg + col);
;                     const f32x4 g0 = {bf_lo(gw.x), bf_hi(gw.x), bf_lo(gw.y), bf_hi(gw.y)}, g1 = {bf_lo(gw.z), bf_hi(gw.z), bf_lo(gw.w), bf_hi(gw.w)};
;                     v0 = v0 * g0; v1 = v1 * g1;
;                     if (MODE == 4) {
;                         const u32x4 ow = *(const GAS1 u32x4*)((const bf16_t*)O + (size_t)row * ldc + col);
;                         const f32x4 o0 = {bf_lo(ow.x), bf_hi(ow.x), bf_lo(ow.y), bf_hi(ow.y)}, o1 = {bf_lo(ow.z), bf_hi(ow.z), bf_lo(ow.w), bf_hi(ow.w)};
;                         v0 += o0; v1 += o1;
;                     }
;                 }
;                 u32x4 w; w.x = cvt_pk_bf16(v0[0], v0[1]); w.y = cvt_pk_bf16(v0[2], v0[3]); w.z = cvt_pk_bf16(v1[0], v1[1]); w.w = cvt_pk_bf16(v1[2], v1[3]);
;                 if (bj == 0) asm volatile("ds_write_b128 %0, %1" :: "v"(wa), "v"(w)); else asm volatile("ds_write_b128 %0, %1 offset:64" :: "v"(wa), "v"(w));
;             }
;             asm volatile("ds_read_b128 %0, %1" : "=&v"(rb[g & 1][0]) : "v"(ra));
;             asm volatile("ds_read_b128 %0, %1 offset:1152" : "=&v"(rb[g & 1][1]) : "v"(ra));
;             if (g >= 1) {
;                 asm volatile("s_waitcnt lgkmcnt(4)" : "+v"(rb[(g - 1) & 1][0]), "+v"(rb[(g - 1) & 1][1]));
;                 bf16_t* ob = obase + (size_t)(((g - 1) >> 2) * HALF + ((g - 1) & 3) * 16) * ldc;
;                 *(GAS1 u32x4*)ob = rb[(g - 1) & 1][0]; *(GAS1 u32x4*)(ob + (size_t)8 * ldc) = rb[(g - 1) & 1][1];
;             }
;         }
;         asm volatile("s_waitcnt lgkmcnt(0)" : "+v"(rb[1][0]), "+v"(rb[1][1]));
;         { bf16_t* ob = obase + (size_t)(HALF + 3 * 16) * ldc; *(GAS1 u32x4*)ob = rb[1][0]; *(GAS1 u32x4*)(ob + (size_t)8 * ldc) = rb[1][1]; }
	v_mov_b32_e32 v24, v240
	v_mov_b32_e32 v25, v241
	v_mov_b32_e32 v26, v242
	v_mov_b32_e32 v27, v243
	v_lshlrev_b32_e32 v42, 16, v24
	v_and_b32_e32 v43, 0xffff0000, v24
	v_lshlrev_b32_e32 v24, 16, v25
	v_and_b32_e32 v25, 0xffff0000, v25
	v_lshlrev_b32_e32 v44, 16, v26
	v_and_b32_e32 v45, 0xffff0000, v26
	v_lshlrev_b32_e32 v26, 16, v27
	v_and_b32_e32 v27, 0xffff0000, v27
	v_pk_mul_f32 v[22:23], v[22:23], v[24:25]
	v_pk_mul_f32 v[24:25], v[14:15], v[26:27]
	v_pk_mul_f32 v[14:15], v[12:13], v[44:45]
	v_pk_mul_f32 v[20:21], v[20:21], v[42:43]
	s_nop 0
	v_cvt_pk_bf16_f32 v12, v20, v21
	v_cvt_pk_bf16_f32 v13, v22, v23
	v_cvt_pk_bf16_f32 v14, v14, v15
	v_cvt_pk_bf16_f32 v15, v24, v25
	s_nop 0
	ds_write_b128 v154, v[12:15] offset:64
	ds_read_b128 v[12:15], v155
	ds_read_b128 v[20:23], v155 offset:1152
	s_waitcnt lgkmcnt(4)
	global_store_dwordx4 v[34:35], v[28:31], off nt
	global_store_dwordx4 v[40:41], v[36:39], off nt
	s_waitcnt vmcnt(13)
	v_mov_b32_e32 v24, v246
	v_mov_b32_e32 v25, v247
	v_mov_b32_e32 v26, v248
	v_mov_b32_e32 v27, v249
	v_lshlrev_b32_e32 v28, 16, v24
	v_and_b32_e32 v29, 0xffff0000, v24
	v_lshlrev_b32_e32 v24, 16, v25
	v_and_b32_e32 v25, 0xffff0000, v25
	v_lshlrev_b32_e32 v30, 16, v26
	v_and_b32_e32 v31, 0xffff0000, v26
	v_lshlrev_b32_e32 v26, 16, v27
	v_and_b32_e32 v27, 0xffff0000, v27
	v_pk_mul_f32 v[18:19], v[18:19], v[24:25]
	v_pk_mul_f32 v[24:25], v[10:11], v[26:27]
	v_pk_mul_f32 v[10:11], v[8:9], v[30:31]
	v_pk_mul_f32 v[16:17], v[16:17], v[28:29]
	s_nop 0
	v_cvt_pk_bf16_f32 v8, v16, v17
	v_cvt_pk_bf16_f32 v9, v18, v19
	v_cvt_pk_bf16_f32 v10, v10, v11
	v_cvt_pk_bf16_f32 v11, v24, v25
	v_add_co_u32_e32 v16, vcc, s84, v104
	ds_write_b128 v154, v[8:11]
	s_nop 0
	v_addc_co_u32_e32 v17, vcc, 0, v105, vcc
	v_add_co_u32_e32 v18, vcc, s85, v104
	s_waitcnt vmcnt(12)
	v_mov_b32_e32 v8, v250
	v_mov_b32_e32 v9, v251
	v_mov_b32_e32 v10, v252
	v_mov_b32_e32 v11, v253
	v_lshlrev_b32_e32 v28, 16, v8
	v_addc_co_u32_e32 v19, vcc, 0, v105, vcc
	v_add_co_u32_e32 v24, vcc, 0xb0000, v104
	v_and_b32_e32 v29, 0xffff0000, v8
	v_lshlrev_b32_e32 v8, 16, v9
	v_and_b32_e32 v9, 0xffff0000, v9
	v_lshlrev_b32_e32 v30, 16, v10
	v_and_b32_e32 v31, 0xffff0000, v10
	v_lshlrev_b32_e32 v10, 16, v11
	v_and_b32_e32 v11, 0xffff0000, v11
	v_addc_co_u32_e32 v25, vcc, 0, v105, vcc
	v_pk_mul_f32 v[6:7], v[6:7], v[8:9]
	v_pk_mul_f32 v[8:9], v[2:3], v[10:11]
	v_pk_mul_f32 v[2:3], v[0:1], v[30:31]
	v_add_co_u32_e32 v26, vcc, 0xb8000, v104
	v_pk_mul_f32 v[4:5], v[4:5], v[28:29]
	s_nop 0
	v_addc_co_u32_e32 v27, vcc, 0, v105, vcc
	v_cvt_pk_bf16_f32 v0, v4, v5
	v_cvt_pk_bf16_f32 v1, v6, v7
	v_cvt_pk_bf16_f32 v2, v2, v3
	v_cvt_pk_bf16_f32 v3, v8, v9
	s_andn2_b64 vcc, exec, s[6:7]
	ds_write_b128 v154, v[0:3] offset:64
	ds_read_b128 v[0:3], v155
	ds_read_b128 v[4:7], v155 offset:1152
	s_waitcnt lgkmcnt(4)
	global_store_dwordx4 v[16:17], v[12:15], off nt
	global_store_dwordx4 v[18:19], v[20:23], off nt
	s_waitcnt lgkmcnt(0)
	s_mov_b64 s[6:7], -1
	global_store_dwordx4 v[24:25], v[0:3], off nt
	global_store_dwordx4 v[26:27], v[4:7], off nt
	s_cbranch_vccnz .LBB0_1399
	s_andn2_b64 vcc, exec, s[16:17]
	s_cbranch_vccnz .LBB0_1398
	s_barrier
	s_branch .LBB0_1398

;     __device__ __forceinline__ void operator()(const f32x4 (&acc)[2][2][4][2], const Unit& u, int wr, int wc, int fr, int fq) const {
;     ...
;         bf16_t* obase = (bf16_t*)O + (size_t)(u.pm * BM + wr * 64 + (L >> 3)) * ldc + u.pn * BM + wc * 64 + 8 * (L & 7);
; #pragma unroll
;         for (int g = 0; g < 8; ++g) {
;             const int ai = g >> 2, m = g & 3;
;             const int row = row0 + ai * HALF + m * 16;
; #pragma unroll
;             for (int bj = 0; bj < 2; ++bj) {
;                 const int col = col0 + bj * 32;
;                 f32x4 v0 = acc[ai][bj][m][0], v1 = acc[ai][bj][m][1];
;                 if (MODE == 1) {
;                     if (special) {
;                         const f32x4 b0 = *(const GAS1 f32x4*)(bias + col) * -1.4426950408889634f, b1 = *(const GAS1 f32x4*)(bias + col + 4) * -1.4426950408889634f;
; #pragma unroll
;                         for (int j = 0; j < 4; ++j) { v0[j] = __builtin_amdgcn_rcpf(1.0f + __builtin_amdgcn_exp2f(__builtin_fmaf(v0[j], -1.4426950408889634f, b0[j])));
;                                                       v1[j] = __builtin_amdgcn_rcpf(1.0f + __builtin_amdgcn_exp2f(__builtin_fmaf(v1[j], -1.4426950408889634f, b1[j]))); }
;                     }
;                 }
;                 if (MODE == 2) {
;                     if (special) {
;                         const int fi = ((col & 63) >> 3) * 4;
;                         const f32x4 c = *(const GAS1 f32x4*)(cosT + (size_t)row * 32 + fi), s_ = *(const GAS1 f32x4*)(sinT + (size_t)row * 32 + fi);
;                         const f32x4 o1 = v0 * c - v1 * s_, o2 = v1 * c + v0 * s_; v0 = o1; v1 = o2;
;                     }
;                 }
;                 if (MODE == 3 || MODE == 4) {
;                     const u32x4 gw = *(const GAS1 u32x4*)(G + (size_t)row * ldg + col);
;                     const f32x4 g0 = {bf_lo(gw.x), bf_hi(gw.x), bf_lo(gw.y), bf_hi(gw.y)}, g1 = {bf_lo(gw.z), bf_hi(gw.z), bf_lo(gw.w), bf_hi(gw.w)};
;                     v0 = v0 * g0; v1 = v1 * g1;
;                     if (MODE == 4) {
;                         const u32x4 ow = *(const GAS1 u32x4*)((const bf16_t*)O + (size_t)row * ldc + col);
;                         const f32x4 o0 = {bf_lo(ow.x), bf_hi(ow.x), bf_lo(ow.y), bf_hi(ow.y)}, o1 = {bf_lo(ow.z), bf_hi(ow.z), bf_lo(ow.w), bf_hi(ow.w)};
;                         v0 += o0; v1 += o1;
;                     }
.LBB0_1434:
	s_lshl_b32 s21, s28, 8
	s_add_i32 s21, s21, s63
	v_or_b32_e32 v148, s21, v152
	s_lshl_b32 s28, s29, 8
	v_or_b32_e32 v146, s28, v155
	v_ashrrev_i32_e32 v149, 31, v148
	v_mov_b64_e32 v[150:151], s[14:15]
	v_ashrrev_i32_e32 v147, 31, v146
	v_lshlrev_b64 v[166:167], 12, v[148:149]
	v_mad_i64_i32 v[162:163], s[30:31], v148, s72, v[150:151]
	v_lshlrev_b64 v[146:147], 1, v[146:147]
	v_lshl_add_u64 v[166:167], s[8:9], 0, v[166:167]
	v_lshl_add_u64 v[176:177], v[162:163], 0, v[146:147]
	v_lshl_add_u64 v[178:179], v[166:167], 0, v[146:147]
	v_add_u32_e32 v254, 0, v148
	v_ashrrev_i32_e32 v255, 31, v254
	v_mad_i64_i32 v[206:207], s[98:99], v254, s72, v[150:151]
	v_lshlrev_b64 v[232:233], 12, v[254:255]
	v_lshl_add_u64 v[206:207], v[206:207], 0, v[146:147]
	v_lshl_add_u64 v[232:233], s[8:9], 0, v[232:233]
	v_lshl_add_u64 v[232:233], v[232:233], 0, v[146:147]
	global_load_dwordx4 v[188:191], v[206:207], off nt
	global_load_dwordx4 v[192:195], v[232:233], off
	global_load_dwordx4 v[196:199], v[206:207], off offset:64 nt
	global_load_dwordx4 v[202:205], v[232:233], off offset:64
	v_add_u32_e32 v254, 16, v148
	v_ashrrev_i32_e32 v255, 31, v254
	v_mad_i64_i32 v[206:207], s[98:99], v254, s72, v[150:151]
	v_lshlrev_b64 v[232:233], 12, v[254:255]
	v_lshl_add_u64 v[206:207], v[206:207], 0, v[146:147]
	v_lshl_add_u64 v[232:233], s[8:9], 0, v[232:233]
	v_lshl_add_u64 v[232:233], v[232:233], 0, v[146:147]
	global_load_dwordx4 v[210:213], v[206:207], off nt
	global_load_dwordx4 v[214:217], v[232:233], off
	global_load_dwordx4 v[218:221], v[206:207], off offset:64 nt
	global_load_dwordx4 v[222:225], v[232:233], off offset:64
	v_add_u32_e32 v254, 32, v148
	v_ashrrev_i32_e32 v255, 31, v254
	v_mad_i64_i32 v[206:207], s[98:99], v254, s72, v[150:151]
	v_lshlrev_b64 v[232:233], 12, v[254:255]
	v_lshl_add_u64 v[206:207], v[206:207], 0, v[146:147]
	v_lshl_add_u64 v[232:233], s[8:9], 0, v[232:233]
	v_lshl_add_u64 v[232:233], v[232:233], 0, v[146:147]
	global_load_dwordx4 v[226:229], v[206:207], off nt
	global_load_dwordx4 v[236:239], v[232:233], off
	global_load_dwordx4 v[240:243], v[206:207], off offset:64 nt
	global_load_dwordx4 v[246:249], v[232:233], off offset:64
	s_ashr_i32 s29, s28, 31
	s_waitcnt vmcnt(10)
	v_mov_b32_e32 v162, v188
	v_mov_b32_e32 v163, v189
	v_mov_b32_e32 v164, v190
	v_mov_b32_e32 v165, v191
	v_mov_b32_e32 v166, v192
	v_mov_b32_e32 v167, v193
	v_mov_b32_e32 v168, v194
	v_mov_b32_e32 v169, v195
	v_lshlrev_b32_e32 v180, 16, v162
	v_and_b32_e32 v181, 0xffff0000, v162
	v_lshlrev_b32_e32 v162, 16, v163
	v_and_b32_e32 v163, 0xffff0000, v163
	v_lshlrev_b32_e32 v182, 16, v164
	v_and_b32_e32 v183, 0xffff0000, v164
	v_lshlrev_b32_e32 v164, 16, v165
	v_and_b32_e32 v165, 0xffff0000, v165
	v_lshlrev_b32_e32 v184, 16, v166
	v_and_b32_e32 v185, 0xffff0000, v166
	v_lshlrev_b32_e32 v166, 16, v167
	v_and_b32_e32 v167, 0xffff0000, v167
	v_lshlrev_b32_e32 v186, 16, v168
	v_and_b32_e32 v187, 0xffff0000, v168
	v_lshlrev_b32_e32 v168, 16, v169
	v_and_b32_e32 v169, 0xffff0000, v169
	v_pk_fma_f32 v[126:127], v[126:127], v[162:163], v[166:167]
	v_pk_fma_f32 v[162:163], v[122:123], v[164:165], v[168:169]
	v_pk_fma_f32 v[122:123], v[120:121], v[182:183], v[186:187]
	v_pk_fma_f32 v[124:125], v[124:125], v[180:181], v[184:185]
	s_nop 0
	v_cvt_pk_bf16_f32 v120, v124, v125
	v_cvt_pk_bf16_f32 v121, v126, v127
	v_cvt_pk_bf16_f32 v122, v122, v123
	v_cvt_pk_bf16_f32 v123, v162, v163
	v_or_b32_e32 v162, 16, v148
	ds_write_b128 v156, v[120:123]
	v_ashrrev_i32_e32 v163, 31, v162
	v_mad_i64_i32 v[164:165], s[30:31], v162, s72, v[150:151]
	v_lshl_add_u64 v[164:165], v[164:165], 0, v[146:147]
	s_waitcnt vmcnt(9)
	v_mov_b32_e32 v120, v196
	v_mov_b32_e32 v121, v197
	v_mov_b32_e32 v122, v198
	v_mov_b32_e32 v123, v199
	v_lshlrev_b32_e32 v166, 16, v120
	v_and_b32_e32 v167, 0xffff0000, v120
	v_lshlrev_b32_e32 v120, 16, v121
	v_and_b32_e32 v121, 0xffff0000, v121
	s_waitcnt vmcnt(8)
	v_mov_b32_e32 v124, v202
	v_mov_b32_e32 v125, v203
	v_mov_b32_e32 v126, v204
	v_mov_b32_e32 v127, v205
	v_lshlrev_b32_e32 v176, 16, v124
	v_and_b32_e32 v177, 0xffff0000, v124
	v_lshlrev_b32_e32 v124, 16, v125
	v_and_b32_e32 v125, 0xffff0000, v125
	v_lshlrev_b32_e32 v168, 16, v122
	v_and_b32_e32 v169, 0xffff0000, v122
	v_lshlrev_b32_e32 v122, 16, v123
	v_and_b32_e32 v123, 0xffff0000, v123
	v_lshlrev_b32_e32 v178, 16, v126
	v_and_b32_e32 v179, 0xffff0000, v126
	v_lshlrev_b32_e32 v126, 16, v127
	v_and_b32_e32 v127, 0xffff0000, v127
	v_pk_fma_f32 v[118:119], v[118:119], v[120:121], v[124:125]
	v_lshlrev_b64 v[124:125], 12, v[162:163]
	v_pk_fma_f32 v[120:121], v[114:115], v[122:123], v[126:127]
	v_pk_fma_f32 v[114:115], v[112:113], v[168:169], v[178:179]
	v_lshl_add_u64 v[124:125], s[8:9], 0, v[124:125]
	v_pk_fma_f32 v[116:117], v[116:117], v[166:167], v[176:177]
	v_lshl_add_u64 v[162:163], v[124:125], 0, v[146:147]
	v_cvt_pk_bf16_f32 v112, v116, v117
	v_cvt_pk_bf16_f32 v113, v118, v119
	v_cvt_pk_bf16_f32 v114, v114, v115
	v_cvt_pk_bf16_f32 v115, v120, v121
	s_nop 0
	ds_write_b128 v156, v[112:115] offset:64
	ds_read_b128 v[112:115], v157
	ds_read_b128 v[116:119], v157 offset:1152
	s_waitcnt vmcnt(7)
	v_mov_b32_e32 v120, v210
	v_mov_b32_e32 v121, v211
	v_mov_b32_e32 v122, v212
	v_mov_b32_e32 v123, v213
	v_lshlrev_b32_e32 v166, 16, v120
	v_and_b32_e32 v167, 0xffff0000, v120
	v_lshlrev_b32_e32 v120, 16, v121
	v_and_b32_e32 v121, 0xffff0000, v121
	v_lshlrev_b32_e32 v168, 16, v122
	v_and_b32_e32 v169, 0xffff0000, v122
	v_lshlrev_b32_e32 v122, 16, v123
	v_and_b32_e32 v123, 0xffff0000, v123
	s_waitcnt vmcnt(6)
; __device__ __forceinline__ unsigned cvt_pk_bf16(float lo, float hi) { unsigned r; asm volatile("v_cvt_pk_bf16_f32 %0, %1, %2" : "=v"(r) : "v"(lo), "v"(hi)); return r; }
; __device__ __forceinline__ float bf_lo(unsigned w) { return __uint_as_float(w << 16); }
; __device__ __forceinline__ float bf_hi(unsigned w) { return __uint_as_float(w & 0xffff0000u); }
; #define GAS1 __attribute__((address_space(1)))
;     __device__ __forceinline__ void operator()(const f32x4 (&acc)[2][2][4][2], const Unit& u, int wr, int wc, int fr, int fq) const {
;     ...
;                 if (MODE == 3 || MODE == 4) {
;                     const u32x4 gw = *(const GAS1 u32x4*)(G + (size_t)row * ldg + col);
;                     const f32x4 g0 = {bf_lo(gw.x), bf_hi(gw.x), bf_lo(gw.y), bf_hi(gw.y)}, g1 = {bf_lo(gw.z), bf_hi(gw.z), bf_lo(gw.w), bf_hi(gw.w)};
;                     v0 = v0 * g0; v1 = v1 * g1;
;                     if (MODE == 4) {
;                         const u32x4 ow = *(const GAS1 u32x4*)((const bf16_t*)O + (size_t)row * ldc + col);
;                         const f32x4 o0 = {bf_lo(ow.x), bf_hi(ow.x), bf_lo(ow.y), bf_hi(ow.y)}, o1 = {bf_lo(ow.z), bf_hi(ow.z), bf_lo(ow.w), bf_hi(ow.w)};
;                         v0 += o0; v1 += o1;
;                     }
;                 }
;                 u32x4 w; w.x = cvt_pk_bf16(v0[0], v0[1]); w.y = cvt_pk_bf16(v0[2], v0[3]); w.z = cvt_pk_bf16(v1[0], v1[1]); w.w = cvt_pk_bf16(v1[2], v1[3]);
;                 if (bj == 0) asm volatile("ds_write_b128 %0, %1" :: "v"(wa), "v"(w)); else asm volatile("ds_write_b128 %0, %1 offset:64" :: "v"(wa), "v"(w));
;             }
;             asm volatile("ds_read_b128 %0, %1" : "=&v"(rb[g & 1][0]) : "v"(ra));
;             asm volatile("ds_read_b128 %0, %1 offset:1152" : "=&v"(rb[g & 1][1]) : "v"(ra));
;             if (g >= 1) {
;                 asm volatile("s_waitcnt lgkmcnt(4)" : "+v"(rb[(g - 1) & 1][0]), "+v"(rb[(g - 1) & 1][1]));
;                 bf16_t* ob = obase + (size_t)(((g - 1) >> 2) * HALF + ((g - 1) & 3) * 16) * ldc;
;                 *(GAS1 u32x4*)ob = rb[(g - 1) & 1][0]; *(GAS1 u32x4*)(ob + (size_t)8 * ldc) = rb[(g - 1) & 1][1];
	v_mov_b32_e32 v124, v214
	v_mov_b32_e32 v125, v215
	v_mov_b32_e32 v126, v216
	v_mov_b32_e32 v127, v217
	v_lshlrev_b32_e32 v176, 16, v124
	v_and_b32_e32 v177, 0xffff0000, v124
	v_lshlrev_b32_e32 v124, 16, v125
	v_and_b32_e32 v125, 0xffff0000, v125
	v_lshlrev_b32_e32 v178, 16, v126
	v_and_b32_e32 v179, 0xffff0000, v126
	v_lshlrev_b32_e32 v126, 16, v127
	v_and_b32_e32 v127, 0xffff0000, v127
	v_pk_fma_f32 v[110:111], v[110:111], v[120:121], v[124:125]
	v_pk_fma_f32 v[120:121], v[106:107], v[122:123], v[126:127]
	v_pk_fma_f32 v[106:107], v[104:105], v[168:169], v[178:179]
	v_pk_fma_f32 v[108:109], v[108:109], v[166:167], v[176:177]
	s_nop 0
	v_cvt_pk_bf16_f32 v104, v108, v109
	v_cvt_pk_bf16_f32 v105, v110, v111
	v_cvt_pk_bf16_f32 v106, v106, v107
	v_cvt_pk_bf16_f32 v107, v120, v121
	v_or_b32_e32 v110, 32, v148
	ds_write_b128 v156, v[104:107]
	v_or_b32_e32 v104, s21, v154
	v_ashrrev_i32_e32 v105, 31, v104
	v_lshlrev_b64 v[104:105], 12, v[104:105]
	v_lshl_add_u64 v[104:105], s[8:9], 0, v[104:105]
	v_lshl_add_u64 v[104:105], s[28:29], 1, v[104:105]
	v_lshl_add_u64 v[104:105], v[104:105], 0, s[10:11]
	v_ashrrev_i32_e32 v111, 31, v110
	v_mad_i64_i32 v[124:125], s[30:31], v110, s72, v[150:151]
	v_lshl_add_u64 v[104:105], v[104:105], 0, v[136:137]
	v_lshlrev_b64 v[110:111], 12, v[110:111]
	v_add_co_u32_e32 v126, vcc, s67, v104
	v_lshl_add_u64 v[110:111], s[8:9], 0, v[110:111]
	v_lshl_add_u64 v[124:125], v[124:125], 0, v[146:147]
	v_addc_co_u32_e32 v127, vcc, 0, v105, vcc
	s_waitcnt vmcnt(5)
	v_mov_b32_e32 v106, v218
	v_mov_b32_e32 v107, v219
	v_mov_b32_e32 v108, v220
	v_mov_b32_e32 v109, v221
	v_lshlrev_b32_e32 v162, 16, v106
	v_and_b32_e32 v163, 0xffff0000, v106
	v_lshlrev_b32_e32 v106, 16, v107
	v_and_b32_e32 v107, 0xffff0000, v107
	v_lshlrev_b32_e32 v164, 16, v108
	v_and_b32_e32 v165, 0xffff0000, v108
	v_lshlrev_b32_e32 v108, 16, v109
	v_and_b32_e32 v109, 0xffff0000, v109
	s_waitcnt vmcnt(4)
	v_mov_b32_e32 v120, v222
	v_mov_b32_e32 v121, v223
	v_mov_b32_e32 v122, v224
	v_mov_b32_e32 v123, v225
	v_lshlrev_b32_e32 v166, 16, v120
	v_and_b32_e32 v167, 0xffff0000, v120
	v_lshlrev_b32_e32 v120, 16, v121
	v_and_b32_e32 v121, 0xffff0000, v121
	v_lshlrev_b32_e32 v168, 16, v122
	v_and_b32_e32 v169, 0xffff0000, v122
	v_lshlrev_b32_e32 v122, 16, v123
	v_and_b32_e32 v123, 0xffff0000, v123
	v_pk_fma_f32 v[102:103], v[102:103], v[106:107], v[120:121]
	v_pk_fma_f32 v[106:107], v[98:99], v[108:109], v[122:123]
	v_pk_fma_f32 v[98:99], v[96:97], v[164:165], v[168:169]
	v_pk_fma_f32 v[100:101], v[100:101], v[162:163], v[166:167]
	s_nop 0
	v_cvt_pk_bf16_f32 v96, v100, v101
	v_cvt_pk_bf16_f32 v97, v102, v103
	v_cvt_pk_bf16_f32 v98, v98, v99
	v_cvt_pk_bf16_f32 v99, v106, v107
	s_nop 0
	ds_write_b128 v156, v[96:99] offset:64
	ds_read_b128 v[96:99], v157
	ds_read_b128 v[100:103], v157 offset:1152
	s_waitcnt lgkmcnt(4)
	global_store_dwordx4 v[104:105], v[112:115], off nt
	global_store_dwordx4 v[126:127], v[116:119], off nt
	v_lshl_add_u64 v[114:115], v[110:111], 0, v[146:147]
	s_waitcnt vmcnt(5)
	v_mov_b32_e32 v106, v226
	v_mov_b32_e32 v107, v227
	v_mov_b32_e32 v108, v228
	v_mov_b32_e32 v109, v229
	v_lshlrev_b32_e32 v116, 16, v106
	v_and_b32_e32 v117, 0xffff0000, v106
	v_lshlrev_b32_e32 v106, 16, v107
	v_and_b32_e32 v107, 0xffff0000, v107
	v_lshlrev_b32_e32 v118, 16, v108
	v_and_b32_e32 v119, 0xffff0000, v108
	v_lshlrev_b32_e32 v108, 16, v109
	v_and_b32_e32 v109, 0xffff0000, v109
	s_waitcnt vmcnt(4)
	v_mov_b32_e32 v110, v236
	v_mov_b32_e32 v111, v237
	v_mov_b32_e32 v112, v238
	v_mov_b32_e32 v113, v239
	v_lshlrev_b32_e32 v120, 16, v110
	v_and_b32_e32 v121, 0xffff0000, v110
	v_lshlrev_b32_e32 v110, 16, v111
	v_and_b32_e32 v111, 0xffff0000, v111
	v_lshlrev_b32_e32 v122, 16, v112
	v_and_b32_e32 v123, 0xffff0000, v112
	v_lshlrev_b32_e32 v112, 16, v113
	v_and_b32_e32 v113, 0xffff0000, v113
	v_pk_fma_f32 v[94:95], v[94:95], v[106:107], v[110:111]
	v_pk_fma_f32 v[106:107], v[90:91], v[108:109], v[112:113]
	v_pk_fma_f32 v[90:91], v[88:89], v[118:119], v[122:123]
	v_pk_fma_f32 v[92:93], v[92:93], v[116:117], v[120:121]
	v_add_co_u32_e32 v110, vcc, s62, v104
	v_cvt_pk_bf16_f32 v88, v92, v93
	v_cvt_pk_bf16_f32 v89, v94, v95
	v_cvt_pk_bf16_f32 v90, v90, v91
	v_cvt_pk_bf16_f32 v91, v106, v107
	v_or_b32_e32 v106, 48, v148
	ds_write_b128 v156, v[88:91]
	v_ashrrev_i32_e32 v107, 31, v106
	v_addc_co_u32_e32 v111, vcc, 0, v105, vcc
	v_mad_i64_i32 v[108:109], s[28:29], v106, s72, v[150:151]
	v_add_co_u32_e32 v112, vcc, s66, v104
	v_lshl_add_u64 v[108:109], v[108:109], 0, v[146:147]
	s_nop 0
	v_addc_co_u32_e32 v113, vcc, 0, v105, vcc
	s_waitcnt vmcnt(3)
	v_mov_b32_e32 v88, v240
	v_mov_b32_e32 v89, v241
	v_mov_b32_e32 v90, v242
	v_mov_b32_e32 v91, v243
	v_lshlrev_b32_e32 v114, 16, v88
	v_and_b32_e32 v115, 0xffff0000, v88
	v_lshlrev_b32_e32 v88, 16, v89
	v_and_b32_e32 v89, 0xffff0000, v89
	v_lshlrev_b32_e32 v116, 16, v90
	v_and_b32_e32 v117, 0xffff0000, v90
	v_lshlrev_b32_e32 v90, 16, v91
	v_and_b32_e32 v91, 0xffff0000, v91
	s_waitcnt vmcnt(2)
; __device__ __forceinline__ unsigned cvt_pk_bf16(float lo, float hi) { unsigned r; asm volatile("v_cvt_pk_bf16_f32 %0, %1, %2" : "=v"(r) : "v"(lo), "v"(hi)); return r; }
; __device__ __forceinline__ float bf_lo(unsigned w) { return __uint_as_float(w << 16); }
; __device__ __forceinline__ float bf_hi(unsigned w) { return __uint_as_float(w & 0xffff0000u); }
; #define GAS1 __attribute__((address_space(1)))
;     __device__ __forceinline__ void operator()(const f32x4 (&acc)[2][2][4][2], const Unit& u, int wr, int wc, int fr, int fq) const {
;     ...
;                 if (MODE == 3 || MODE == 4) {
;                     const u32x4 gw = *(const GAS1 u32x4*)(G + (size_t)row * ldg + col);
;                     const f32x4 g0 = {bf_lo(gw.x), bf_hi(gw.x), bf_lo(gw.y), bf_hi(gw.y)}, g1 = {bf_lo(gw.z), bf_hi(gw.z), bf_lo(gw.w), bf_hi(gw.w)};
;                     v0 = v0 * g0; v1 = v1 * g1;
;                     if (MODE == 4) {
;                         const u32x4 ow = *(const GAS1 u32x4*)((const bf16_t*)O + (size_t)row * ldc + col);
;                         const f32x4 o0 = {bf_lo(ow.x), bf_hi(ow.x), bf_lo(ow.y), bf_hi(ow.y)}, o1 = {bf_lo(ow.z), bf_hi(ow.z), bf_lo(ow.w), bf_hi(ow.w)};
;                         v0 += o0; v1 += o1;
;                     }
;                 }
;                 u32x4 w; w.x = cvt_pk_bf16(v0[0], v0[1]); w.y = cvt_pk_bf16(v0[2], v0[3]); w.z = cvt_pk_bf16(v1[0], v1[1]); w.w = cvt_pk_bf16(v1[2], v1[3]);
;                 if (bj == 0) asm volatile("ds_write_b128 %0, %1" :: "v"(wa), "v"(w)); else asm volatile("ds_write_b128 %0, %1 offset:64" :: "v"(wa), "v"(w));
;             }
;             asm volatile("ds_read_b128 %0, %1" : "=&v"(rb[g & 1][0]) : "v"(ra));
;             asm volatile("ds_read_b128 %0, %1 offset:1152" : "=&v"(rb[g & 1][1]) : "v"(ra));
;             if (g >= 1) {
;                 asm volatile("s_waitcnt lgkmcnt(4)" : "+v"(rb[(g - 1) & 1][0]), "+v"(rb[(g - 1) & 1][1]));
;                 bf16_t* ob = obase + (size_t)(((g - 1) >> 2) * HALF + ((g - 1) & 3) * 16) * ldc;
;                 *(GAS1 u32x4*)ob = rb[(g - 1) & 1][0]; *(GAS1 u32x4*)(ob + (size_t)8 * ldc) = rb[(g - 1) & 1][1];
	v_mov_b32_e32 v92, v246
	v_mov_b32_e32 v93, v247
	v_mov_b32_e32 v94, v248
	v_mov_b32_e32 v95, v249
	v_add_u32_e32 v254, 48, v148
	v_ashrrev_i32_e32 v255, 31, v254
	v_mad_i64_i32 v[206:207], s[98:99], v254, s72, v[150:151]
	v_lshlrev_b64 v[232:233], 12, v[254:255]
	v_lshl_add_u64 v[206:207], v[206:207], 0, v[146:147]
	v_lshl_add_u64 v[232:233], s[8:9], 0, v[232:233]
	v_lshl_add_u64 v[232:233], v[232:233], 0, v[146:147]
	global_load_dwordx4 v[188:191], v[206:207], off nt
	global_load_dwordx4 v[192:195], v[232:233], off
	global_load_dwordx4 v[196:199], v[206:207], off offset:64 nt
	global_load_dwordx4 v[202:205], v[232:233], off offset:64
	v_add_u32_e32 v254, 128, v148
	v_ashrrev_i32_e32 v255, 31, v254
	v_mad_i64_i32 v[206:207], s[98:99], v254, s72, v[150:151]
	v_lshlrev_b64 v[232:233], 12, v[254:255]
	v_lshl_add_u64 v[206:207], v[206:207], 0, v[146:147]
	v_lshl_add_u64 v[232:233], s[8:9], 0, v[232:233]
	v_lshl_add_u64 v[232:233], v[232:233], 0, v[146:147]
	global_load_dwordx4 v[210:213], v[206:207], off nt
	global_load_dwordx4 v[214:217], v[232:233], off
	global_load_dwordx4 v[218:221], v[206:207], off offset:64 nt
	global_load_dwordx4 v[222:225], v[232:233], off offset:64
	v_add_u32_e32 v254, 144, v148
	v_ashrrev_i32_e32 v255, 31, v254
	v_mad_i64_i32 v[206:207], s[98:99], v254, s72, v[150:151]
	v_lshlrev_b64 v[232:233], 12, v[254:255]
	v_lshl_add_u64 v[206:207], v[206:207], 0, v[146:147]
	v_lshl_add_u64 v[232:233], s[8:9], 0, v[232:233]
	v_lshl_add_u64 v[232:233], v[232:233], 0, v[146:147]
	global_load_dwordx4 v[226:229], v[206:207], off nt
	global_load_dwordx4 v[236:239], v[232:233], off
	global_load_dwordx4 v[240:243], v[206:207], off offset:64 nt
	global_load_dwordx4 v[246:249], v[232:233], off offset:64
	v_lshlrev_b32_e32 v118, 16, v92
	v_and_b32_e32 v119, 0xffff0000, v92
	v_lshlrev_b32_e32 v92, 16, v93
	v_and_b32_e32 v93, 0xffff0000, v93
	v_lshlrev_b32_e32 v120, 16, v94
	v_and_b32_e32 v121, 0xffff0000, v94
	v_lshlrev_b32_e32 v94, 16, v95
	v_and_b32_e32 v95, 0xffff0000, v95
	v_pk_fma_f32 v[86:87], v[86:87], v[88:89], v[92:93]
	v_pk_fma_f32 v[88:89], v[82:83], v[90:91], v[94:95]
	v_pk_fma_f32 v[82:83], v[80:81], v[116:117], v[120:121]
	v_pk_fma_f32 v[84:85], v[84:85], v[114:115], v[118:119]
	v_lshlrev_b64 v[92:93], 12, v[106:107]
	v_cvt_pk_bf16_f32 v80, v84, v85
	v_cvt_pk_bf16_f32 v81, v86, v87
	v_cvt_pk_bf16_f32 v82, v82, v83
	v_cvt_pk_bf16_f32 v83, v88, v89
	v_lshl_add_u64 v[92:93], s[8:9], 0, v[92:93]
	ds_write_b128 v156, v[80:83] offset:64
	ds_read_b128 v[80:83], v157
	ds_read_b128 v[84:87], v157 offset:1152
	s_waitcnt lgkmcnt(4)
	global_store_dwordx4 v[110:111], v[96:99], off nt
	global_store_dwordx4 v[112:113], v[100:103], off nt
	v_lshl_add_u64 v[96:97], v[92:93], 0, v[146:147]
	s_waitcnt vmcnt(13)
	v_mov_b32_e32 v88, v188
	v_mov_b32_e32 v89, v189
	v_mov_b32_e32 v90, v190
	v_mov_b32_e32 v91, v191
	v_lshlrev_b32_e32 v98, 16, v88
	v_and_b32_e32 v99, 0xffff0000, v88
	v_lshlrev_b32_e32 v88, 16, v89
	v_and_b32_e32 v89, 0xffff0000, v89
	v_lshlrev_b32_e32 v100, 16, v90
	v_and_b32_e32 v101, 0xffff0000, v90
	v_lshlrev_b32_e32 v90, 16, v91
	v_and_b32_e32 v91, 0xffff0000, v91
	s_waitcnt vmcnt(12)
	v_mov_b32_e32 v92, v192
	v_mov_b32_e32 v93, v193
	v_mov_b32_e32 v94, v194
	v_mov_b32_e32 v95, v195
	v_lshlrev_b32_e32 v102, 16, v92
	v_and_b32_e32 v103, 0xffff0000, v92
	v_lshlrev_b32_e32 v92, 16, v93
	v_and_b32_e32 v93, 0xffff0000, v93
	v_lshlrev_b32_e32 v106, 16, v94
	v_and_b32_e32 v107, 0xffff0000, v94
	v_lshlrev_b32_e32 v94, 16, v95
	v_and_b32_e32 v95, 0xffff0000, v95
	v_pk_fma_f32 v[78:79], v[78:79], v[88:89], v[92:93]
	v_pk_fma_f32 v[88:89], v[74:75], v[90:91], v[94:95]
	v_pk_fma_f32 v[74:75], v[72:73], v[100:101], v[106:107]
	v_pk_fma_f32 v[76:77], v[76:77], v[98:99], v[102:103]
	v_add_co_u32_e32 v92, vcc, s73, v104
	v_cvt_pk_bf16_f32 v72, v76, v77
	v_cvt_pk_bf16_f32 v73, v78, v79
	v_cvt_pk_bf16_f32 v74, v74, v75
	v_cvt_pk_bf16_f32 v75, v88, v89
	v_add_u32_e32 v88, 0x80, v148
	ds_write_b128 v156, v[72:75]
	v_ashrrev_i32_e32 v89, 31, v88
	v_addc_co_u32_e32 v93, vcc, 0, v105, vcc
	v_mad_i64_i32 v[90:91], s[28:29], v88, s72, v[150:151]
	v_add_co_u32_e32 v94, vcc, s74, v104
	v_lshl_add_u64 v[90:91], v[90:91], 0, v[146:147]
	s_nop 0
	v_addc_co_u32_e32 v95, vcc, 0, v105, vcc
	s_waitcnt vmcnt(11)
	v_mov_b32_e32 v72, v196
	v_mov_b32_e32 v73, v197
	v_mov_b32_e32 v74, v198
	v_mov_b32_e32 v75, v199
	v_lshlrev_b32_e32 v96, 16, v72
	v_and_b32_e32 v97, 0xffff0000, v72
	v_lshlrev_b32_e32 v72, 16, v73
	v_and_b32_e32 v73, 0xffff0000, v73
	v_lshlrev_b32_e32 v98, 16, v74
	v_and_b32_e32 v99, 0xffff0000, v74
	v_lshlrev_b32_e32 v74, 16, v75
	v_and_b32_e32 v75, 0xffff0000, v75
	s_waitcnt vmcnt(10)
	v_mov_b32_e32 v76, v202
	v_mov_b32_e32 v77, v203
	v_mov_b32_e32 v78, v204
	v_mov_b32_e32 v79, v205
	v_lshlrev_b32_e32 v100, 16, v76
	v_and_b32_e32 v101, 0xffff0000, v76
	v_lshlrev_b32_e32 v76, 16, v77
	v_and_b32_e32 v77, 0xffff0000, v77
	v_lshlrev_b32_e32 v102, 16, v78
	v_and_b32_e32 v103, 0xffff0000, v78
	v_lshlrev_b32_e32 v78, 16, v79
	v_and_b32_e32 v79, 0xffff0000, v79
	v_pk_fma_f32 v[70:71], v[70:71], v[72:73], v[76:77]
	v_pk_fma_f32 v[72:73], v[66:67], v[74:75], v[78:79]
	v_pk_fma_f32 v[66:67], v[64:65], v[98:99], v[102:103]
	v_pk_fma_f32 v[68:69], v[68:69], v[96:97], v[100:101]
	v_lshlrev_b64 v[76:77], 12, v[88:89]
	v_cvt_pk_bf16_f32 v64, v68, v69
	v_cvt_pk_bf16_f32 v65, v70, v71
	v_cvt_pk_bf16_f32 v66, v66, v67
	v_cvt_pk_bf16_f32 v67, v72, v73
	v_lshl_add_u64 v[76:77], s[8:9], 0, v[76:77]
	ds_write_b128 v156, v[64:67] offset:64
	ds_read_b128 v[64:67], v157
	ds_read_b128 v[68:71], v157 offset:1152
	s_waitcnt lgkmcnt(4)
; __device__ __forceinline__ unsigned cvt_pk_bf16(float lo, float hi) { unsigned r; asm volatile("v_cvt_pk_bf16_f32 %0, %1, %2" : "=v"(r) : "v"(lo), "v"(hi)); return r; }
; __device__ __forceinline__ float bf_lo(unsigned w) { return __uint_as_float(w << 16); }
; __device__ __forceinline__ float bf_hi(unsigned w) { return __uint_as_float(w & 0xffff0000u); }
; #define GAS1 __attribute__((address_space(1)))
;     __device__ __forceinline__ void operator()(const f32x4 (&acc)[2][2][4][2], const Unit& u, int wr, int wc, int fr, int fq) const {
;     ...
;                 if (MODE == 3 || MODE == 4) {
;                     const u32x4 gw = *(const GAS1 u32x4*)(G + (size_t)row * ldg + col);
;                     const f32x4 g0 = {bf_lo(gw.x), bf_hi(gw.x), bf_lo(gw.y), bf_hi(gw.y)}, g1 = {bf_lo(gw.z), bf_hi(gw.z), bf_lo(gw.w), bf_hi(gw.w)};
;                     v0 = v0 * g0; v1 = v1 * g1;
;                     if (MODE == 4) {
;                         const u32x4 ow = *(const GAS1 u32x4*)((const bf16_t*)O + (size_t)row * ldc + col);
;                         const f32x4 o0 = {bf_lo(ow.x), bf_hi(ow.x), bf_lo(ow.y), bf_hi(ow.y)}, o1 = {bf_lo(ow.z), bf_hi(ow.z), bf_lo(ow.w), bf_hi(ow.w)};
;                         v0 += o0; v1 += o1;
;                     }
;                 }
;                 u32x4 w; w.x = cvt_pk_bf16(v0[0], v0[1]); w.y = cvt_pk_bf16(v0[2], v0[3]); w.z = cvt_pk_bf16(v1[0], v1[1]); w.w = cvt_pk_bf16(v1[2], v1[3]);
;                 if (bj == 0) asm volatile("ds_write_b128 %0, %1" :: "v"(wa), "v"(w)); else asm volatile("ds_write_b128 %0, %1 offset:64" :: "v"(wa), "v"(w));
;             }
;             asm volatile("ds_read_b128 %0, %1" : "=&v"(rb[g & 1][0]) : "v"(ra));
;             asm volatile("ds_read_b128 %0, %1 offset:1152" : "=&v"(rb[g & 1][1]) : "v"(ra));
;             if (g >= 1) {
;                 asm volatile("s_waitcnt lgkmcnt(4)" : "+v"(rb[(g - 1) & 1][0]), "+v"(rb[(g - 1) & 1][1]));
;                 bf16_t* ob = obase + (size_t)(((g - 1) >> 2) * HALF + ((g - 1) & 3) * 16) * ldc;
;                 *(GAS1 u32x4*)ob = rb[(g - 1) & 1][0]; *(GAS1 u32x4*)(ob + (size_t)8 * ldc) = rb[(g - 1) & 1][1];
	global_store_dwordx4 v[92:93], v[80:83], off nt
	global_store_dwordx4 v[94:95], v[84:87], off nt
	v_lshl_add_u64 v[80:81], v[76:77], 0, v[146:147]
	s_waitcnt vmcnt(11)
	v_mov_b32_e32 v72, v210
	v_mov_b32_e32 v73, v211
	v_mov_b32_e32 v74, v212
	v_mov_b32_e32 v75, v213
	v_lshlrev_b32_e32 v82, 16, v72
	v_and_b32_e32 v83, 0xffff0000, v72
	v_lshlrev_b32_e32 v72, 16, v73
	v_and_b32_e32 v73, 0xffff0000, v73
	v_lshlrev_b32_e32 v84, 16, v74
	v_and_b32_e32 v85, 0xffff0000, v74
	v_lshlrev_b32_e32 v74, 16, v75
	v_and_b32_e32 v75, 0xffff0000, v75
	s_waitcnt vmcnt(10)
	v_mov_b32_e32 v76, v214
	v_mov_b32_e32 v77, v215
	v_mov_b32_e32 v78, v216
	v_mov_b32_e32 v79, v217
	v_lshlrev_b32_e32 v86, 16, v76
	v_and_b32_e32 v87, 0xffff0000, v76
	v_lshlrev_b32_e32 v76, 16, v77
	v_and_b32_e32 v77, 0xffff0000, v77
	v_lshlrev_b32_e32 v88, 16, v78
	v_and_b32_e32 v89, 0xffff0000, v78
	v_lshlrev_b32_e32 v78, 16, v79
	v_and_b32_e32 v79, 0xffff0000, v79
	v_pk_fma_f32 v[62:63], v[62:63], v[72:73], v[76:77]
	v_pk_fma_f32 v[72:73], v[58:59], v[74:75], v[78:79]
	v_pk_fma_f32 v[58:59], v[56:57], v[84:85], v[88:89]
	v_pk_fma_f32 v[60:61], v[60:61], v[82:83], v[86:87]
	v_add_co_u32_e32 v76, vcc, s75, v104
	v_cvt_pk_bf16_f32 v56, v60, v61
	v_cvt_pk_bf16_f32 v57, v62, v63
	v_cvt_pk_bf16_f32 v58, v58, v59
	v_cvt_pk_bf16_f32 v59, v72, v73
	v_add_u32_e32 v72, 0x90, v148
	ds_write_b128 v156, v[56:59]
	v_ashrrev_i32_e32 v73, 31, v72
	v_addc_co_u32_e32 v77, vcc, 0, v105, vcc
	v_mad_i64_i32 v[74:75], s[28:29], v72, s72, v[150:151]
	v_add_co_u32_e32 v78, vcc, s76, v104
	v_lshl_add_u64 v[74:75], v[74:75], 0, v[146:147]
	s_nop 0
	v_addc_co_u32_e32 v79, vcc, 0, v105, vcc
	s_waitcnt vmcnt(9)
	v_mov_b32_e32 v56, v218
	v_mov_b32_e32 v57, v219
	v_mov_b32_e32 v58, v220
	v_mov_b32_e32 v59, v221
	v_lshlrev_b32_e32 v80, 16, v56
	v_and_b32_e32 v81, 0xffff0000, v56
	v_lshlrev_b32_e32 v56, 16, v57
	v_and_b32_e32 v57, 0xffff0000, v57
	v_lshlrev_b32_e32 v82, 16, v58
	v_and_b32_e32 v83, 0xffff0000, v58
	v_lshlrev_b32_e32 v58, 16, v59
	v_and_b32_e32 v59, 0xffff0000, v59
	s_waitcnt vmcnt(8)
	v_mov_b32_e32 v60, v222
	v_mov_b32_e32 v61, v223
	v_mov_b32_e32 v62, v224
	v_mov_b32_e32 v63, v225
	v_lshlrev_b32_e32 v84, 16, v60
	v_and_b32_e32 v85, 0xffff0000, v60
	v_lshlrev_b32_e32 v60, 16, v61
	v_and_b32_e32 v61, 0xffff0000, v61
	v_lshlrev_b32_e32 v86, 16, v62
	v_and_b32_e32 v87, 0xffff0000, v62
	v_lshlrev_b32_e32 v62, 16, v63
	v_and_b32_e32 v63, 0xffff0000, v63
	v_pk_fma_f32 v[54:55], v[54:55], v[56:57], v[60:61]
	v_pk_fma_f32 v[56:57], v[50:51], v[58:59], v[62:63]
	v_pk_fma_f32 v[50:51], v[48:49], v[82:83], v[86:87]
	v_pk_fma_f32 v[52:53], v[52:53], v[80:81], v[84:85]
	v_lshlrev_b64 v[60:61], 12, v[72:73]
	v_cvt_pk_bf16_f32 v48, v52, v53
	v_cvt_pk_bf16_f32 v49, v54, v55
	v_cvt_pk_bf16_f32 v50, v50, v51
	v_cvt_pk_bf16_f32 v51, v56, v57
	v_lshl_add_u64 v[60:61], s[8:9], 0, v[60:61]
	ds_write_b128 v156, v[48:51] offset:64
	ds_read_b128 v[48:51], v157
	ds_read_b128 v[52:55], v157 offset:1152
	s_waitcnt lgkmcnt(4)
	global_store_dwordx4 v[76:77], v[64:67], off nt
	global_store_dwordx4 v[78:79], v[68:71], off nt
	v_lshl_add_u64 v[64:65], v[60:61], 0, v[146:147]
	s_waitcnt vmcnt(9)
	v_mov_b32_e32 v56, v226
	v_mov_b32_e32 v57, v227
	v_mov_b32_e32 v58, v228
	v_mov_b32_e32 v59, v229
	v_lshlrev_b32_e32 v66, 16, v56
	v_and_b32_e32 v67, 0xffff0000, v56
	v_lshlrev_b32_e32 v56, 16, v57
	v_and_b32_e32 v57, 0xffff0000, v57
	v_lshlrev_b32_e32 v68, 16, v58
	v_and_b32_e32 v69, 0xffff0000, v58
	v_lshlrev_b32_e32 v58, 16, v59
	v_and_b32_e32 v59, 0xffff0000, v59
	s_waitcnt vmcnt(8)
	v_mov_b32_e32 v60, v236
	v_mov_b32_e32 v61, v237
	v_mov_b32_e32 v62, v238
	v_mov_b32_e32 v63, v239
	v_lshlrev_b32_e32 v70, 16, v60
	v_and_b32_e32 v71, 0xffff0000, v60
	v_lshlrev_b32_e32 v60, 16, v61
	v_and_b32_e32 v61, 0xffff0000, v61
	v_lshlrev_b32_e32 v72, 16, v62
	v_and_b32_e32 v73, 0xffff0000, v62
	v_lshlrev_b32_e32 v62, 16, v63
	v_and_b32_e32 v63, 0xffff0000, v63
	v_pk_fma_f32 v[46:47], v[46:47], v[56:57], v[60:61]
	v_pk_fma_f32 v[56:57], v[42:43], v[58:59], v[62:63]
	v_pk_fma_f32 v[42:43], v[40:41], v[68:69], v[72:73]
	v_pk_fma_f32 v[44:45], v[44:45], v[66:67], v[70:71]
	v_add_co_u32_e32 v60, vcc, s77, v104
	v_cvt_pk_bf16_f32 v40, v44, v45
	v_cvt_pk_bf16_f32 v41, v46, v47
	v_cvt_pk_bf16_f32 v42, v42, v43
	v_cvt_pk_bf16_f32 v43, v56, v57
	v_add_u32_e32 v56, 0xa0, v148
	ds_write_b128 v156, v[40:43]
	v_ashrrev_i32_e32 v57, 31, v56
	v_addc_co_u32_e32 v61, vcc, 0, v105, vcc
	v_mad_i64_i32 v[58:59], s[28:29], v56, s72, v[150:151]
	v_add_co_u32_e32 v62, vcc, s79, v104
	v_lshl_add_u64 v[58:59], v[58:59], 0, v[146:147]
	s_nop 0
	v_addc_co_u32_e32 v63, vcc, 0, v105, vcc
	s_waitcnt vmcnt(7)
	v_mov_b32_e32 v40, v240
	v_mov_b32_e32 v41, v241
	v_mov_b32_e32 v42, v242
	v_mov_b32_e32 v43, v243
	v_lshlrev_b32_e32 v64, 16, v40
	v_and_b32_e32 v65, 0xffff0000, v40
	v_lshlrev_b32_e32 v40, 16, v41
	v_and_b32_e32 v41, 0xffff0000, v41
	v_lshlrev_b32_e32 v66, 16, v42
	v_and_b32_e32 v67, 0xffff0000, v42
	v_lshlrev_b32_e32 v42, 16, v43
	v_and_b32_e32 v43, 0xffff0000, v43
	s_waitcnt vmcnt(6)
; __device__ __forceinline__ unsigned cvt_pk_bf16(float lo, float hi) { unsigned r; asm volatile("v_cvt_pk_bf16_f32 %0, %1, %2" : "=v"(r) : "v"(lo), "v"(hi)); return r; }
; __device__ __forceinline__ float bf_lo(unsigned w) { return __uint_as_float(w << 16); }
; __device__ __forceinline__ float bf_hi(unsigned w) { return __uint_as_float(w & 0xffff0000u); }
; #define GAS1 __attribute__((address_space(1)))
;     __device__ __forceinline__ void operator()(const f32x4 (&acc)[2][2][4][2], const Unit& u, int wr, int wc, int fr, int fq) const {
;     ...
;                 if (MODE == 3 || MODE == 4) {
;                     const u32x4 gw = *(const GAS1 u32x4*)(G + (size_t)row * ldg + col);
;                     const f32x4 g0 = {bf_lo(gw.x), bf_hi(gw.x), bf_lo(gw.y), bf_hi(gw.y)}, g1 = {bf_lo(gw.z), bf_hi(gw.z), bf_lo(gw.w), bf_hi(gw.w)};
;                     v0 = v0 * g0; v1 = v1 * g1;
;                     if (MODE == 4) {
;                         const u32x4 ow = *(const GAS1 u32x4*)((const bf16_t*)O + (size_t)row * ldc + col);
;                         const f32x4 o0 = {bf_lo(ow.x), bf_hi(ow.x), bf_lo(ow.y), bf_hi(ow.y)}, o1 = {bf_lo(ow.z), bf_hi(ow.z), bf_lo(ow.w), bf_hi(ow.w)};
;                         v0 += o0; v1 += o1;
;                     }
;                 }
;                 u32x4 w; w.x = cvt_pk_bf16(v0[0], v0[1]); w.y = cvt_pk_bf16(v0[2], v0[3]); w.z = cvt_pk_bf16(v1[0], v1[1]); w.w = cvt_pk_bf16(v1[2], v1[3]);
;                 if (bj == 0) asm volatile("ds_write_b128 %0, %1" :: "v"(wa), "v"(w)); else asm volatile("ds_write_b128 %0, %1 offset:64" :: "v"(wa), "v"(w));
;             }
;             asm volatile("ds_read_b128 %0, %1" : "=&v"(rb[g & 1][0]) : "v"(ra));
;             asm volatile("ds_read_b128 %0, %1 offset:1152" : "=&v"(rb[g & 1][1]) : "v"(ra));
;             if (g >= 1) {
;                 asm volatile("s_waitcnt lgkmcnt(4)" : "+v"(rb[(g - 1) & 1][0]), "+v"(rb[(g - 1) & 1][1]));
;                 bf16_t* ob = obase + (size_t)(((g - 1) >> 2) * HALF + ((g - 1) & 3) * 16) * ldc;
;                 *(GAS1 u32x4*)ob = rb[(g - 1) & 1][0]; *(GAS1 u32x4*)(ob + (size_t)8 * ldc) = rb[(g - 1) & 1][1];
	v_mov_b32_e32 v44, v246
	v_mov_b32_e32 v45, v247
	v_mov_b32_e32 v46, v248
	v_mov_b32_e32 v47, v249
	v_add_u32_e32 v254, 160, v148
	v_ashrrev_i32_e32 v255, 31, v254
	v_mad_i64_i32 v[206:207], s[98:99], v254, s72, v[150:151]
	v_lshlrev_b64 v[232:233], 12, v[254:255]
	v_lshl_add_u64 v[206:207], v[206:207], 0, v[146:147]
	v_lshl_add_u64 v[232:233], s[8:9], 0, v[232:233]
	v_lshl_add_u64 v[232:233], v[232:233], 0, v[146:147]
	global_load_dwordx4 v[188:191], v[206:207], off nt
	global_load_dwordx4 v[192:195], v[232:233], off
	global_load_dwordx4 v[196:199], v[206:207], off offset:64 nt
	global_load_dwordx4 v[202:205], v[232:233], off offset:64
	v_add_u32_e32 v254, 176, v148
	v_ashrrev_i32_e32 v255, 31, v254
	v_mad_i64_i32 v[206:207], s[98:99], v254, s72, v[150:151]
	v_lshlrev_b64 v[232:233], 12, v[254:255]
	v_lshl_add_u64 v[206:207], v[206:207], 0, v[146:147]
	v_lshl_add_u64 v[232:233], s[8:9], 0, v[232:233]
	v_lshl_add_u64 v[232:233], v[232:233], 0, v[146:147]
	global_load_dwordx4 v[210:213], v[206:207], off nt
	global_load_dwordx4 v[214:217], v[232:233], off
	global_load_dwordx4 v[218:221], v[206:207], off offset:64 nt
	global_load_dwordx4 v[222:225], v[232:233], off offset:64
	v_lshlrev_b32_e32 v68, 16, v44
	v_and_b32_e32 v69, 0xffff0000, v44
	v_lshlrev_b32_e32 v44, 16, v45
	v_and_b32_e32 v45, 0xffff0000, v45
	v_lshlrev_b32_e32 v70, 16, v46
	v_and_b32_e32 v71, 0xffff0000, v46
	v_lshlrev_b32_e32 v46, 16, v47
	v_and_b32_e32 v47, 0xffff0000, v47
	v_pk_fma_f32 v[38:39], v[38:39], v[40:41], v[44:45]
	v_pk_fma_f32 v[40:41], v[34:35], v[42:43], v[46:47]
	v_pk_fma_f32 v[34:35], v[32:33], v[66:67], v[70:71]
	v_pk_fma_f32 v[36:37], v[36:37], v[64:65], v[68:69]
	v_lshlrev_b64 v[44:45], 12, v[56:57]
	v_cvt_pk_bf16_f32 v32, v36, v37
	v_cvt_pk_bf16_f32 v33, v38, v39
	v_cvt_pk_bf16_f32 v34, v34, v35
	v_cvt_pk_bf16_f32 v35, v40, v41
	v_lshl_add_u64 v[44:45], s[8:9], 0, v[44:45]
	ds_write_b128 v156, v[32:35] offset:64
	ds_read_b128 v[32:35], v157
	ds_read_b128 v[36:39], v157 offset:1152
	s_waitcnt lgkmcnt(4)
	global_store_dwordx4 v[60:61], v[48:51], off nt
	global_store_dwordx4 v[62:63], v[52:55], off nt
	v_lshl_add_u64 v[48:49], v[44:45], 0, v[146:147]
	s_waitcnt vmcnt(9)
	v_mov_b32_e32 v40, v188
	v_mov_b32_e32 v41, v189
	v_mov_b32_e32 v42, v190
	v_mov_b32_e32 v43, v191
	v_lshlrev_b32_e32 v50, 16, v40
	v_and_b32_e32 v51, 0xffff0000, v40
	v_lshlrev_b32_e32 v40, 16, v41
	v_and_b32_e32 v41, 0xffff0000, v41
	v_lshlrev_b32_e32 v52, 16, v42
	v_and_b32_e32 v53, 0xffff0000, v42
	v_lshlrev_b32_e32 v42, 16, v43
	v_and_b32_e32 v43, 0xffff0000, v43
	s_waitcnt vmcnt(8)
	v_mov_b32_e32 v44, v192
	v_mov_b32_e32 v45, v193
	v_mov_b32_e32 v46, v194
	v_mov_b32_e32 v47, v195
	v_lshlrev_b32_e32 v54, 16, v44
	v_and_b32_e32 v55, 0xffff0000, v44
	v_lshlrev_b32_e32 v44, 16, v45
	v_and_b32_e32 v45, 0xffff0000, v45
	v_lshlrev_b32_e32 v56, 16, v46
	v_and_b32_e32 v57, 0xffff0000, v46
	v_lshlrev_b32_e32 v46, 16, v47
	v_and_b32_e32 v47, 0xffff0000, v47
	v_pk_fma_f32 v[30:31], v[30:31], v[40:41], v[44:45]
	v_pk_fma_f32 v[40:41], v[26:27], v[42:43], v[46:47]
	v_pk_fma_f32 v[26:27], v[24:25], v[52:53], v[56:57]
	v_pk_fma_f32 v[28:29], v[28:29], v[50:51], v[54:55]
	v_add_co_u32_e32 v44, vcc, s80, v104
	v_cvt_pk_bf16_f32 v24, v28, v29
	v_cvt_pk_bf16_f32 v25, v30, v31
	v_cvt_pk_bf16_f32 v26, v26, v27
	v_cvt_pk_bf16_f32 v27, v40, v41
	v_add_u32_e32 v40, 0xb0, v148
	ds_write_b128 v156, v[24:27]
	v_ashrrev_i32_e32 v41, 31, v40
	v_addc_co_u32_e32 v45, vcc, 0, v105, vcc
	v_mad_i64_i32 v[42:43], s[28:29], v40, s72, v[150:151]
	v_add_co_u32_e32 v46, vcc, s81, v104
	v_lshl_add_u64 v[42:43], v[42:43], 0, v[146:147]
	s_nop 0
	v_addc_co_u32_e32 v47, vcc, 0, v105, vcc
	s_waitcnt vmcnt(7)
	v_mov_b32_e32 v24, v196
	v_mov_b32_e32 v25, v197
	v_mov_b32_e32 v26, v198
	v_mov_b32_e32 v27, v199
	v_lshlrev_b32_e32 v48, 16, v24
	v_and_b32_e32 v49, 0xffff0000, v24
	v_lshlrev_b32_e32 v24, 16, v25
	v_and_b32_e32 v25, 0xffff0000, v25
	v_lshlrev_b32_e32 v50, 16, v26
	v_and_b32_e32 v51, 0xffff0000, v26
	v_lshlrev_b32_e32 v26, 16, v27
	v_and_b32_e32 v27, 0xffff0000, v27
	s_waitcnt vmcnt(6)
; __device__ __forceinline__ unsigned cvt_pk_bf16(float lo, float hi) { unsigned r; asm volatile("v_cvt_pk_bf16_f32 %0, %1, %2" : "=v"(r) : "v"(lo), "v"(hi)); return r; }
; __device__ __forceinline__ float bf_lo(unsigned w) { return __uint_as_float(w << 16); }
; __device__ __forceinline__ float bf_hi(unsigned w) { return __uint_as_float(w & 0xffff0000u); }
; #define GAS1 __attribute__((address_space(1)))
;     __device__ __forceinline__ void operator()(const f32x4 (&acc)[2][2][4][2], const Unit& u, int wr, int wc, int fr, int fq) const {
;     ...
;                 if (MODE == 3 || MODE == 4) {
;                     const u32x4 gw = *(const GAS1 u32x4*)(G + (size_t)row * ldg + col);
;                     const f32x4 g0 = {bf_lo(gw.x), bf_hi(gw.x), bf_lo(gw.y), bf_hi(gw.y)}, g1 = {bf_lo(gw.z), bf_hi(gw.z), bf_lo(gw.w), bf_hi(gw.w)};
;                     v0 = v0 * g0; v1 = v1 * g1;
;                     if (MODE == 4) {
;                         const u32x4 ow = *(const GAS1 u32x4*)((const bf16_t*)O + (size_t)row * ldc + col);
;                         const f32x4 o0 = {bf_lo(ow.x), bf_hi(ow.x), bf_lo(ow.y), bf_hi(ow.y)}, o1 = {bf_lo(ow.z), bf_hi(ow.z), bf_lo(ow.w), bf_hi(ow.w)};
;                         v0 += o0; v1 += o1;
;                     }
;                 }
;                 u32x4 w; w.x = cvt_pk_bf16(v0[0], v0[1]); w.y = cvt_pk_bf16(v0[2], v0[3]); w.z = cvt_pk_bf16(v1[0], v1[1]); w.w = cvt_pk_bf16(v1[2], v1[3]);
;                 if (bj == 0) asm volatile("ds_write_b128 %0, %1" :: "v"(wa), "v"(w)); else asm volatile("ds_write_b128 %0, %1 offset:64" :: "v"(wa), "v"(w));
;             }
;             asm volatile("ds_read_b128 %0, %1" : "=&v"(rb[g & 1][0]) : "v"(ra));
;             asm volatile("ds_read_b128 %0, %1 offset:1152" : "=&v"(rb[g & 1][1]) : "v"(ra));
;             if (g >= 1) {
;                 asm volatile("s_waitcnt lgkmcnt(4)" : "+v"(rb[(g - 1) & 1][0]), "+v"(rb[(g - 1) & 1][1]));
;                 bf16_t* ob = obase + (size_t)(((g - 1) >> 2) * HALF + ((g - 1) & 3) * 16) * ldc;
;                 *(GAS1 u32x4*)ob = rb[(g - 1) & 1][0]; *(GAS1 u32x4*)(ob + (size_t)8 * ldc) = rb[(g - 1) & 1][1];
;             }
;         }
;         asm volatile("s_waitcnt lgkmcnt(0)" : "+v"(rb[1][0]), "+v"(rb[1][1]));
;         { bf16_t* ob = obase + (size_t)(HALF + 3 * 16) * ldc; *(GAS1 u32x4*)ob = rb[1][0]; *(GAS1 u32x4*)(ob + (size_t)8 * ldc) = rb[1][1]; }
	v_mov_b32_e32 v28, v202
	v_mov_b32_e32 v29, v203
	v_mov_b32_e32 v30, v204
	v_mov_b32_e32 v31, v205
	v_lshlrev_b32_e32 v52, 16, v28
	v_and_b32_e32 v53, 0xffff0000, v28
	v_lshlrev_b32_e32 v28, 16, v29
	v_and_b32_e32 v29, 0xffff0000, v29
	v_lshlrev_b32_e32 v54, 16, v30
	v_and_b32_e32 v55, 0xffff0000, v30
	v_lshlrev_b32_e32 v30, 16, v31
	v_and_b32_e32 v31, 0xffff0000, v31
	v_pk_fma_f32 v[22:23], v[22:23], v[24:25], v[28:29]
	v_pk_fma_f32 v[24:25], v[18:19], v[26:27], v[30:31]
	v_pk_fma_f32 v[18:19], v[16:17], v[50:51], v[54:55]
	v_pk_fma_f32 v[20:21], v[20:21], v[48:49], v[52:53]
	v_lshlrev_b64 v[28:29], 12, v[40:41]
	v_cvt_pk_bf16_f32 v16, v20, v21
	v_cvt_pk_bf16_f32 v17, v22, v23
	v_cvt_pk_bf16_f32 v18, v18, v19
	v_cvt_pk_bf16_f32 v19, v24, v25
	v_lshl_add_u64 v[28:29], s[8:9], 0, v[28:29]
	ds_write_b128 v156, v[16:19] offset:64
	ds_read_b128 v[16:19], v157
	ds_read_b128 v[20:23], v157 offset:1152
	s_waitcnt lgkmcnt(4)
	global_store_dwordx4 v[44:45], v[32:35], off nt
	global_store_dwordx4 v[46:47], v[36:39], off nt
	v_lshl_add_u64 v[32:33], v[28:29], 0, v[146:147]
	s_waitcnt vmcnt(7)
	v_mov_b32_e32 v24, v210
	v_mov_b32_e32 v25, v211
	v_mov_b32_e32 v26, v212
	v_mov_b32_e32 v27, v213
	v_lshlrev_b32_e32 v34, 16, v24
	v_and_b32_e32 v35, 0xffff0000, v24
	v_lshlrev_b32_e32 v24, 16, v25
	v_and_b32_e32 v25, 0xffff0000, v25
	v_lshlrev_b32_e32 v36, 16, v26
	v_and_b32_e32 v37, 0xffff0000, v26
	v_lshlrev_b32_e32 v26, 16, v27
	v_and_b32_e32 v27, 0xffff0000, v27
	s_waitcnt vmcnt(6)
	v_mov_b32_e32 v28, v214
	v_mov_b32_e32 v29, v215
	v_mov_b32_e32 v30, v216
	v_mov_b32_e32 v31, v217
	v_lshlrev_b32_e32 v38, 16, v28
	v_and_b32_e32 v39, 0xffff0000, v28
	v_lshlrev_b32_e32 v28, 16, v29
	v_and_b32_e32 v29, 0xffff0000, v29
	v_lshlrev_b32_e32 v40, 16, v30
	v_and_b32_e32 v41, 0xffff0000, v30
	v_lshlrev_b32_e32 v30, 16, v31
	v_and_b32_e32 v31, 0xffff0000, v31
	v_pk_fma_f32 v[14:15], v[14:15], v[24:25], v[28:29]
	v_pk_fma_f32 v[24:25], v[10:11], v[26:27], v[30:31]
	v_pk_fma_f32 v[10:11], v[8:9], v[36:37], v[40:41]
	v_pk_fma_f32 v[12:13], v[12:13], v[34:35], v[38:39]
	s_nop 0
	v_cvt_pk_bf16_f32 v8, v12, v13
	v_cvt_pk_bf16_f32 v9, v14, v15
	v_cvt_pk_bf16_f32 v10, v10, v11
	v_cvt_pk_bf16_f32 v11, v24, v25
	v_add_co_u32_e32 v24, vcc, s82, v104
	ds_write_b128 v156, v[8:11]
	v_addc_co_u32_e32 v25, vcc, 0, v105, vcc
	v_add_co_u32_e32 v26, vcc, s83, v104
	s_waitcnt vmcnt(5)
	v_mov_b32_e32 v8, v218
	v_mov_b32_e32 v9, v219
	v_mov_b32_e32 v10, v220
	v_mov_b32_e32 v11, v221
	v_lshlrev_b32_e32 v32, 16, v8
	v_addc_co_u32_e32 v27, vcc, 0, v105, vcc
	v_add_co_u32_e32 v28, vcc, 0xb0000, v104
	v_and_b32_e32 v33, 0xffff0000, v8
	v_lshlrev_b32_e32 v8, 16, v9
	v_and_b32_e32 v9, 0xffff0000, v9
	v_lshlrev_b32_e32 v34, 16, v10
	v_and_b32_e32 v35, 0xffff0000, v10
	v_lshlrev_b32_e32 v10, 16, v11
	v_and_b32_e32 v11, 0xffff0000, v11
	s_waitcnt vmcnt(4)
	v_mov_b32_e32 v12, v222
	v_mov_b32_e32 v13, v223
	v_mov_b32_e32 v14, v224
	v_mov_b32_e32 v15, v225
	v_lshlrev_b32_e32 v36, 16, v12
	v_and_b32_e32 v37, 0xffff0000, v12
	v_lshlrev_b32_e32 v12, 16, v13
	v_and_b32_e32 v13, 0xffff0000, v13
	v_lshlrev_b32_e32 v38, 16, v14
	v_and_b32_e32 v39, 0xffff0000, v14
	v_lshlrev_b32_e32 v14, 16, v15
	v_and_b32_e32 v15, 0xffff0000, v15
	v_addc_co_u32_e32 v29, vcc, 0, v105, vcc
	v_pk_fma_f32 v[6:7], v[6:7], v[8:9], v[12:13]
	v_pk_fma_f32 v[8:9], v[2:3], v[10:11], v[14:15]
	v_pk_fma_f32 v[2:3], v[0:1], v[34:35], v[38:39]
	v_add_co_u32_e32 v30, vcc, 0xb8000, v104
	v_pk_fma_f32 v[4:5], v[4:5], v[32:33], v[36:37]
	s_nop 0
	v_addc_co_u32_e32 v31, vcc, 0, v105, vcc
	v_cvt_pk_bf16_f32 v0, v4, v5
	v_cvt_pk_bf16_f32 v1, v6, v7
	v_cvt_pk_bf16_f32 v2, v2, v3
	v_cvt_pk_bf16_f32 v3, v8, v9
	s_andn2_b64 vcc, exec, s[6:7]
	ds_write_b128 v156, v[0:3] offset:64
	ds_read_b128 v[0:3], v157
	ds_read_b128 v[4:7], v157 offset:1152
	s_waitcnt lgkmcnt(4)
	global_store_dwordx4 v[24:25], v[16:19], off nt
	global_store_dwordx4 v[26:27], v[20:23], off nt
	s_waitcnt lgkmcnt(0)
	s_mov_b64 s[6:7], -1
	global_store_dwordx4 v[28:29], v[0:3], off nt
	global_store_dwordx4 v[30:31], v[4:7], off nt
	s_cbranch_vccnz .LBB0_1423
	s_andn2_b64 vcc, exec, s[12:13]
	s_cbranch_vccnz .LBB0_1422
	s_barrier
	s_branch .LBB0_1422
